# attention: the two d=16 tiles of a wave run as one job; the softmax arithmetic of one tile is spread over the other tile's K / V streaming steps
# speedup vs baseline: 1.0451x; 1.0038x over previous
.Latt_noedge_4:
	s_nop 1
	v_max3_f32 v186, v36, v37, v38
	v_max3_f32 v186, v186, v39, v40
	v_max3_f32 v186, v186, v41, v42
	v_max3_f32 v186, v186, v43, v44
	v_max3_f32 v186, v186, v45, v46
	v_max3_f32 v186, v186, v47, v48
	v_max3_f32 v186, v186, v49, v50
	v_max3_f32 v186, v186, v51, v52
	v_max3_f32 v186, v186, v53, v54
	v_max3_f32 v186, v186, v55, v56
	v_max3_f32 v186, v186, v57, v58
	v_max3_f32 v186, v186, v59, v60
	v_max3_f32 v186, v186, v61, v62
	v_max3_f32 v186, v186, v63, v64
	v_max3_f32 v186, v186, v65, v66
	v_max3_f32 v186, v186, v67, v68
	v_max3_f32 v186, v186, v69, v70
	v_max_f32_e32 v186, v186, v71
	v_mov_b32_e32 v146, v186
	s_nop 1
	v_permlane16_swap_b32_e32 v186, v146
	v_max_f32_e32 v186, v186, v146
	v_mov_b32_e32 v146, v186
	s_nop 1
	v_permlane32_swap_b32_e32 v186, v146
	v_max_f32_e32 v186, v186, v146
	v_pk_add_f32 v[36:37], v[36:37], v[186:187] op_sel_hi:[1,0] neg_lo:[0,1] neg_hi:[0,1]
	v_pk_add_f32 v[38:39], v[38:39], v[186:187] op_sel_hi:[1,0] neg_lo:[0,1] neg_hi:[0,1]
	v_pk_add_f32 v[40:41], v[40:41], v[186:187] op_sel_hi:[1,0] neg_lo:[0,1] neg_hi:[0,1]
	v_pk_add_f32 v[42:43], v[42:43], v[186:187] op_sel_hi:[1,0] neg_lo:[0,1] neg_hi:[0,1]
	v_exp_f32_e32 v36, v36
	v_exp_f32_e32 v37, v37
	v_exp_f32_e32 v38, v38
	v_exp_f32_e32 v39, v39
	v_pk_add_f32 v[44:45], v[44:45], v[186:187] op_sel_hi:[1,0] neg_lo:[0,1] neg_hi:[0,1]
	v_pk_add_f32 v[46:47], v[46:47], v[186:187] op_sel_hi:[1,0] neg_lo:[0,1] neg_hi:[0,1]
	v_exp_f32_e32 v40, v40
	v_exp_f32_e32 v41, v41
	v_exp_f32_e32 v42, v42
	v_exp_f32_e32 v43, v43
	v_pk_add_f32 v[48:49], v[48:49], v[186:187] op_sel_hi:[1,0] neg_lo:[0,1] neg_hi:[0,1]
	v_pk_add_f32 v[50:51], v[50:51], v[186:187] op_sel_hi:[1,0] neg_lo:[0,1] neg_hi:[0,1]
	v_exp_f32_e32 v44, v44
	v_exp_f32_e32 v45, v45
	v_exp_f32_e32 v46, v46
	v_exp_f32_e32 v47, v47
	v_pk_add_f32 v[52:53], v[52:53], v[186:187] op_sel_hi:[1,0] neg_lo:[0,1] neg_hi:[0,1]
	v_pk_add_f32 v[54:55], v[54:55], v[186:187] op_sel_hi:[1,0] neg_lo:[0,1] neg_hi:[0,1]
	v_exp_f32_e32 v48, v48
	v_exp_f32_e32 v49, v49
	v_exp_f32_e32 v50, v50
	v_exp_f32_e32 v51, v51
	v_pk_add_f32 v[56:57], v[56:57], v[186:187] op_sel_hi:[1,0] neg_lo:[0,1] neg_hi:[0,1]
	v_pk_add_f32 v[58:59], v[58:59], v[186:187] op_sel_hi:[1,0] neg_lo:[0,1] neg_hi:[0,1]
	v_exp_f32_e32 v52, v52
	v_exp_f32_e32 v53, v53
	v_exp_f32_e32 v54, v54
	v_exp_f32_e32 v55, v55
	v_pk_add_f32 v[60:61], v[60:61], v[186:187] op_sel_hi:[1,0] neg_lo:[0,1] neg_hi:[0,1]
	v_pk_add_f32 v[62:63], v[62:63], v[186:187] op_sel_hi:[1,0] neg_lo:[0,1] neg_hi:[0,1]
	v_exp_f32_e32 v56, v56
	v_exp_f32_e32 v57, v57
	v_exp_f32_e32 v58, v58
	v_exp_f32_e32 v59, v59
	v_pk_add_f32 v[64:65], v[64:65], v[186:187] op_sel_hi:[1,0] neg_lo:[0,1] neg_hi:[0,1]
	v_pk_add_f32 v[66:67], v[66:67], v[186:187] op_sel_hi:[1,0] neg_lo:[0,1] neg_hi:[0,1]
	v_exp_f32_e32 v60, v60
	v_exp_f32_e32 v61, v61
	v_exp_f32_e32 v62, v62
	v_exp_f32_e32 v63, v63
	v_pk_add_f32 v[68:69], v[68:69], v[186:187] op_sel_hi:[1,0] neg_lo:[0,1] neg_hi:[0,1]
	v_pk_add_f32 v[70:71], v[70:71], v[186:187] op_sel_hi:[1,0] neg_lo:[0,1] neg_hi:[0,1]
	v_exp_f32_e32 v64, v64
	v_exp_f32_e32 v65, v65
	v_exp_f32_e32 v66, v66
	v_exp_f32_e32 v67, v67
	v_exp_f32_e32 v68, v68
	v_exp_f32_e32 v69, v69
	v_exp_f32_e32 v70, v70
	v_exp_f32_e32 v71, v71
	s_nop 0
	v_pk_add_f32 v[146:147], v[36:37], v[38:39]
	v_pk_add_f32 v[148:149], v[40:41], v[42:43]
	v_pk_add_f32 v[146:147], v[146:147], v[44:45]
	v_pk_add_f32 v[148:149], v[148:149], v[46:47]
	v_pk_add_f32 v[146:147], v[146:147], v[48:49]
	v_pk_add_f32 v[148:149], v[148:149], v[50:51]
	v_pk_add_f32 v[146:147], v[146:147], v[52:53]
	v_pk_add_f32 v[148:149], v[148:149], v[54:55]
	v_pk_add_f32 v[146:147], v[146:147], v[56:57]
	v_pk_add_f32 v[148:149], v[148:149], v[58:59]
	v_pk_add_f32 v[146:147], v[146:147], v[60:61]
	v_pk_add_f32 v[148:149], v[148:149], v[62:63]
	v_pk_add_f32 v[146:147], v[146:147], v[64:65]
	v_pk_add_f32 v[148:149], v[148:149], v[66:67]
	v_pk_add_f32 v[146:147], v[146:147], v[68:69]
	v_pk_add_f32 v[148:149], v[148:149], v[70:71]
	s_nop 0
	v_pk_add_f32 v[146:147], v[146:147], v[148:149]
	s_nop 0
	v_add_f32_e32 v187, v146, v147
	v_cvt_pk_bf16_f32 v36, v36, v37
	v_cvt_pk_bf16_f32 v37, v38, v39
	v_cvt_pk_bf16_f32 v40, v40, v41
	v_cvt_pk_bf16_f32 v41, v42, v43
	v_cvt_pk_bf16_f32 v44, v44, v45
	v_cvt_pk_bf16_f32 v45, v46, v47
	v_cvt_pk_bf16_f32 v48, v48, v49
	v_cvt_pk_bf16_f32 v49, v50, v51
	v_cvt_pk_bf16_f32 v52, v52, v53
	v_cvt_pk_bf16_f32 v53, v54, v55
	v_cvt_pk_bf16_f32 v56, v56, v57
	v_cvt_pk_bf16_f32 v57, v58, v59
	v_cvt_pk_bf16_f32 v60, v60, v61
	v_cvt_pk_bf16_f32 v61, v62, v63
	v_cvt_pk_bf16_f32 v64, v64, v65
	v_cvt_pk_bf16_f32 v65, v66, v67
	v_cvt_pk_bf16_f32 v68, v68, v69
	v_cvt_pk_bf16_f32 v69, v70, v71
	v_mov_b32_e32 v146, v187
	s_nop 1
	v_permlane16_swap_b32_e32 v187, v146
	v_add_f32_e32 v187, v187, v146
	v_mov_b32_e32 v146, v187
	s_nop 1
	v_permlane32_swap_b32_e32 v187, v146
	v_add_f32_e32 v187, v187, v146
	s_waitcnt lgkmcnt(0)
	s_add_i32 s93, s76, 64
	s_mov_b32 m0, s16
	v_add_u32_e32 v164, s93, v231
	v_med3_i32 v164, v164, 0, s40
	v_lshl_or_b32 v164, v164, 7, v222
	global_load_lds_dwordx4 v164, s[24:25]
	s_add_i32 m0, s16, 0x400
	v_add_u32_e32 v165, s93, v232
	v_med3_i32 v165, v165, 0, s40
	v_lshl_or_b32 v165, v165, 7, v222
	global_load_lds_dwordx4 v165, s[24:25]
	s_waitcnt vmcnt(8)
	v_add_u32_e32 v154, s12, v225
	v_add_u32_e32 v155, s12, v226
	v_add_u32_e32 v156, s12, v227
	v_add_u32_e32 v157, s12, v228
	ds_read_b64_tr_b16 v[202:203], v154
	ds_read_b64_tr_b16 v[204:205], v155
	ds_read_b64_tr_b16 v[206:207], v156
	ds_read_b64_tr_b16 v[208:209], v157
	v_mfma_f32_16x16x16_bf16 v[96:99], v[88:89], v[0:1], 0
	v_mfma_f32_16x16x16_bf16 v[100:103], v[90:91], v[0:1], 0
	v_mfma_f32_16x16x16_bf16 v[104:107], v[92:93], v[0:1], 0
	v_mfma_f32_16x16x16_bf16 v[108:111], v[94:95], v[0:1], 0
	s_waitcnt lgkmcnt(0)
	s_add_i32 s93, s76, 0x80
	s_mov_b32 m0, s12
	v_add_u32_e32 v164, s93, v231
	v_med3_i32 v164, v164, 0, s40
	v_lshl_or_b32 v164, v164, 7, v222
	global_load_lds_dwordx4 v164, s[24:25]
	s_add_i32 m0, s12, 0x400
	v_add_u32_e32 v165, s93, v232
	v_med3_i32 v165, v165, 0, s40
	v_lshl_or_b32 v165, v165, 7, v222
	global_load_lds_dwordx4 v165, s[24:25]
	s_waitcnt vmcnt(8)
	v_add_u32_e32 v154, s13, v225
	v_add_u32_e32 v155, s13, v226
	v_add_u32_e32 v156, s13, v227
	v_add_u32_e32 v157, s13, v228
	ds_read_b64_tr_b16 v[88:89], v154
	ds_read_b64_tr_b16 v[90:91], v155
	ds_read_b64_tr_b16 v[92:93], v156
	ds_read_b64_tr_b16 v[94:95], v157
	v_mfma_f32_16x16x16_bf16 v[96:99], v[202:203], v[4:5], v[96:99]
	v_mfma_f32_16x16x16_bf16 v[112:115], v[202:203], v[36:37], 0
	v_mfma_f32_16x16x16_bf16 v[100:103], v[204:205], v[4:5], v[100:103]
	v_mfma_f32_16x16x16_bf16 v[116:119], v[204:205], v[36:37], 0
	v_mfma_f32_16x16x16_bf16 v[104:107], v[206:207], v[4:5], v[104:107]
	v_mfma_f32_16x16x16_bf16 v[120:123], v[206:207], v[36:37], 0
	v_mfma_f32_16x16x16_bf16 v[108:111], v[208:209], v[4:5], v[108:111]
	v_mfma_f32_16x16x16_bf16 v[124:127], v[208:209], v[36:37], 0
	s_waitcnt lgkmcnt(0)
	s_add_i32 s93, s76, 0xc0
	s_mov_b32 m0, s13
	v_add_u32_e32 v164, s93, v231
	v_med3_i32 v164, v164, 0, s40
	v_lshl_or_b32 v164, v164, 7, v222
	global_load_lds_dwordx4 v164, s[24:25]
	s_add_i32 m0, s13, 0x400
	v_add_u32_e32 v165, s93, v232
	v_med3_i32 v165, v165, 0, s40
	v_lshl_or_b32 v165, v165, 7, v222
	global_load_lds_dwordx4 v165, s[24:25]
	s_waitcnt vmcnt(8)
	v_add_u32_e32 v154, s14, v225
	v_add_u32_e32 v155, s14, v226
	v_add_u32_e32 v156, s14, v227
	v_add_u32_e32 v157, s14, v228
	ds_read_b64_tr_b16 v[202:203], v154
	ds_read_b64_tr_b16 v[204:205], v155
	ds_read_b64_tr_b16 v[206:207], v156
	ds_read_b64_tr_b16 v[208:209], v157
	v_mfma_f32_16x16x16_bf16 v[96:99], v[88:89], v[8:9], v[96:99]
	v_mfma_f32_16x16x16_bf16 v[112:115], v[88:89], v[40:41], v[112:115]
	v_mfma_f32_16x16x16_bf16 v[100:103], v[90:91], v[8:9], v[100:103]
	v_mfma_f32_16x16x16_bf16 v[116:119], v[90:91], v[40:41], v[116:119]
	v_mfma_f32_16x16x16_bf16 v[104:107], v[92:93], v[8:9], v[104:107]
	v_mfma_f32_16x16x16_bf16 v[120:123], v[92:93], v[40:41], v[120:123]
	v_mfma_f32_16x16x16_bf16 v[108:111], v[94:95], v[8:9], v[108:111]
	v_mfma_f32_16x16x16_bf16 v[124:127], v[94:95], v[40:41], v[124:127]
	s_waitcnt lgkmcnt(0)
	s_add_i32 s93, s76, 0x100
	s_mov_b32 m0, s14
	v_add_u32_e32 v164, s93, v231
	v_med3_i32 v164, v164, 0, s40
	v_lshl_or_b32 v164, v164, 7, v222
	global_load_lds_dwordx4 v164, s[24:25]
	s_add_i32 m0, s14, 0x400
	v_add_u32_e32 v165, s93, v232
	v_med3_i32 v165, v165, 0, s40
	v_lshl_or_b32 v165, v165, 7, v222
	global_load_lds_dwordx4 v165, s[24:25]
	s_waitcnt vmcnt(8)
	v_add_u32_e32 v154, s15, v225
	v_add_u32_e32 v155, s15, v226
	v_add_u32_e32 v156, s15, v227
	v_add_u32_e32 v157, s15, v228
	ds_read_b64_tr_b16 v[88:89], v154
	ds_read_b64_tr_b16 v[90:91], v155
	ds_read_b64_tr_b16 v[92:93], v156
	ds_read_b64_tr_b16 v[94:95], v157
	v_mfma_f32_16x16x16_bf16 v[96:99], v[202:203], v[12:13], v[96:99]
	v_mfma_f32_16x16x16_bf16 v[112:115], v[202:203], v[44:45], v[112:115]
	v_mfma_f32_16x16x16_bf16 v[100:103], v[204:205], v[12:13], v[100:103]
	v_mfma_f32_16x16x16_bf16 v[116:119], v[204:205], v[44:45], v[116:119]
	v_mfma_f32_16x16x16_bf16 v[104:107], v[206:207], v[12:13], v[104:107]
	v_mfma_f32_16x16x16_bf16 v[120:123], v[206:207], v[44:45], v[120:123]
	v_mfma_f32_16x16x16_bf16 v[108:111], v[208:209], v[12:13], v[108:111]
	v_mfma_f32_16x16x16_bf16 v[124:127], v[208:209], v[44:45], v[124:127]
	s_waitcnt lgkmcnt(0)
	s_add_i32 s93, s76, 0x140
	s_mov_b32 m0, s15
	v_add_u32_e32 v164, s93, v231
	v_med3_i32 v164, v164, 0, s40
	v_lshl_or_b32 v164, v164, 7, v222
	global_load_lds_dwordx4 v164, s[24:25]
	s_add_i32 m0, s15, 0x400
	v_add_u32_e32 v165, s93, v232
	v_med3_i32 v165, v165, 0, s40
	v_lshl_or_b32 v165, v165, 7, v222
	global_load_lds_dwordx4 v165, s[24:25]
	s_waitcnt vmcnt(8)
	v_add_u32_e32 v154, s16, v225
	v_add_u32_e32 v155, s16, v226
	v_add_u32_e32 v156, s16, v227
	v_add_u32_e32 v157, s16, v228
	ds_read_b64_tr_b16 v[202:203], v154
	ds_read_b64_tr_b16 v[204:205], v155
	ds_read_b64_tr_b16 v[206:207], v156
	ds_read_b64_tr_b16 v[208:209], v157
	v_mfma_f32_16x16x16_bf16 v[96:99], v[88:89], v[16:17], v[96:99]
	v_mfma_f32_16x16x16_bf16 v[112:115], v[88:89], v[48:49], v[112:115]
	v_mfma_f32_16x16x16_bf16 v[100:103], v[90:91], v[16:17], v[100:103]
	v_mfma_f32_16x16x16_bf16 v[116:119], v[90:91], v[48:49], v[116:119]
	v_mfma_f32_16x16x16_bf16 v[104:107], v[92:93], v[16:17], v[104:107]
	v_mfma_f32_16x16x16_bf16 v[120:123], v[92:93], v[48:49], v[120:123]
	v_mfma_f32_16x16x16_bf16 v[108:111], v[94:95], v[16:17], v[108:111]
	v_mfma_f32_16x16x16_bf16 v[124:127], v[94:95], v[48:49], v[124:127]
	s_waitcnt lgkmcnt(0)
	s_add_i32 s93, s79, 0
	s_mov_b32 m0, s16
	v_add_u32_e32 v164, s93, v162
	v_lshl_or_b32 v164, v164, 7, v220
	global_load_lds_dwordx4 v164, s[18:19]
	s_add_i32 m0, s16, 0x400
	v_add_u32_e32 v165, s93, v163
	v_lshl_or_b32 v165, v165, 7, v221
	global_load_lds_dwordx4 v165, s[18:19]
	s_waitcnt vmcnt(8)
	v_add_u32_e32 v154, s12, v225
	v_add_u32_e32 v155, s12, v226
	v_add_u32_e32 v156, s12, v227
	v_add_u32_e32 v157, s12, v228
	ds_read_b64_tr_b16 v[88:89], v154
	ds_read_b64_tr_b16 v[90:91], v155
	ds_read_b64_tr_b16 v[92:93], v156
	ds_read_b64_tr_b16 v[94:95], v157
	v_mfma_f32_16x16x16_bf16 v[96:99], v[202:203], v[20:21], v[96:99]
	v_mfma_f32_16x16x16_bf16 v[112:115], v[202:203], v[52:53], v[112:115]
	v_mfma_f32_16x16x16_bf16 v[100:103], v[204:205], v[20:21], v[100:103]
	v_mfma_f32_16x16x16_bf16 v[116:119], v[204:205], v[52:53], v[116:119]
	v_mfma_f32_16x16x16_bf16 v[104:107], v[206:207], v[20:21], v[104:107]
	v_mfma_f32_16x16x16_bf16 v[120:123], v[206:207], v[52:53], v[120:123]
	v_mfma_f32_16x16x16_bf16 v[108:111], v[208:209], v[20:21], v[108:111]
	v_mfma_f32_16x16x16_bf16 v[124:127], v[208:209], v[52:53], v[124:127]
	s_waitcnt lgkmcnt(0)
	s_add_i32 s93, s79, 0xfffffc00
	s_mov_b32 m0, s12
	v_add_u32_e32 v164, s93, v162
	v_med3_i32 v164, v164, 0, s40
	v_lshl_or_b32 v164, v164, 7, v220
	global_load_lds_dwordx4 v164, s[20:21]
	s_add_i32 m0, s12, 0x400
	v_add_u32_e32 v165, s93, v163
	v_med3_i32 v165, v165, 0, s40
	v_lshl_or_b32 v165, v165, 7, v221
	global_load_lds_dwordx4 v165, s[20:21]
	s_waitcnt vmcnt(8)
	v_add_u32_e32 v154, s13, v225
	v_add_u32_e32 v155, s13, v226
	v_add_u32_e32 v156, s13, v227
	v_add_u32_e32 v157, s13, v228
	ds_read_b64_tr_b16 v[202:203], v154
	ds_read_b64_tr_b16 v[204:205], v155
	ds_read_b64_tr_b16 v[206:207], v156
	ds_read_b64_tr_b16 v[208:209], v157
	v_mfma_f32_16x16x16_bf16 v[96:99], v[88:89], v[24:25], v[96:99]
	v_mfma_f32_16x16x16_bf16 v[112:115], v[88:89], v[56:57], v[112:115]
	v_mfma_f32_16x16x16_bf16 v[100:103], v[90:91], v[24:25], v[100:103]
	v_mfma_f32_16x16x16_bf16 v[116:119], v[90:91], v[56:57], v[116:119]
	v_mfma_f32_16x16x16_bf16 v[104:107], v[92:93], v[24:25], v[104:107]
	v_mfma_f32_16x16x16_bf16 v[120:123], v[92:93], v[56:57], v[120:123]
	v_mfma_f32_16x16x16_bf16 v[108:111], v[94:95], v[24:25], v[108:111]
	v_mfma_f32_16x16x16_bf16 v[124:127], v[94:95], v[56:57], v[124:127]
	s_waitcnt lgkmcnt(0)
	s_add_i32 s93, s79, 0xfffffd00
	s_mov_b32 m0, s13
	v_add_u32_e32 v164, s93, v162
	v_med3_i32 v164, v164, 0, s40
	v_lshl_or_b32 v164, v164, 7, v220
	global_load_lds_dwordx4 v164, s[20:21]
	s_add_i32 m0, s13, 0x400
	v_add_u32_e32 v165, s93, v163
	v_med3_i32 v165, v165, 0, s40
	v_lshl_or_b32 v165, v165, 7, v221
	global_load_lds_dwordx4 v165, s[20:21]
	s_waitcnt vmcnt(8)
	v_add_u32_e32 v154, s14, v225
	v_add_u32_e32 v155, s14, v226
	v_add_u32_e32 v156, s14, v227
	v_add_u32_e32 v157, s14, v228
	ds_read_b64_tr_b16 v[88:89], v154
	ds_read_b64_tr_b16 v[90:91], v155
	ds_read_b64_tr_b16 v[92:93], v156
	ds_read_b64_tr_b16 v[94:95], v157
	v_mfma_f32_16x16x16_bf16 v[96:99], v[202:203], v[28:29], v[96:99]
	v_mfma_f32_16x16x16_bf16 v[112:115], v[202:203], v[60:61], v[112:115]
	v_mfma_f32_16x16x16_bf16 v[100:103], v[204:205], v[28:29], v[100:103]
	v_mfma_f32_16x16x16_bf16 v[116:119], v[204:205], v[60:61], v[116:119]
	v_mfma_f32_16x16x16_bf16 v[104:107], v[206:207], v[28:29], v[104:107]
	v_mfma_f32_16x16x16_bf16 v[120:123], v[206:207], v[60:61], v[120:123]
	v_mfma_f32_16x16x16_bf16 v[108:111], v[208:209], v[28:29], v[108:111]
	v_mfma_f32_16x16x16_bf16 v[124:127], v[208:209], v[60:61], v[124:127]
	s_waitcnt lgkmcnt(0)
	s_add_i32 s93, s79, 0xfffffe00
	s_mov_b32 m0, s14
	v_add_u32_e32 v164, s93, v162
	v_med3_i32 v164, v164, 0, s40
	v_lshl_or_b32 v164, v164, 7, v220
	global_load_lds_dwordx4 v164, s[20:21]
	s_add_i32 m0, s14, 0x400
	v_add_u32_e32 v165, s93, v163
	v_med3_i32 v165, v165, 0, s40
	v_lshl_or_b32 v165, v165, 7, v221
	global_load_lds_dwordx4 v165, s[20:21]
	s_waitcnt vmcnt(8)
	v_add_u32_e32 v154, s15, v225
	v_add_u32_e32 v155, s15, v226
	v_add_u32_e32 v156, s15, v227
	v_add_u32_e32 v157, s15, v228
	ds_read_b64_tr_b16 v[202:203], v154
	ds_read_b64_tr_b16 v[204:205], v155
	ds_read_b64_tr_b16 v[206:207], v156
	ds_read_b64_tr_b16 v[208:209], v157
	v_mfma_f32_16x16x16_bf16 v[96:99], v[88:89], v[32:33], v[96:99]
	v_mfma_f32_16x16x16_bf16 v[112:115], v[88:89], v[64:65], v[112:115]
	v_mfma_f32_16x16x16_bf16 v[100:103], v[90:91], v[32:33], v[100:103]
	v_mfma_f32_16x16x16_bf16 v[116:119], v[90:91], v[64:65], v[116:119]
	v_mfma_f32_16x16x16_bf16 v[104:107], v[92:93], v[32:33], v[104:107]
	v_mfma_f32_16x16x16_bf16 v[120:123], v[92:93], v[64:65], v[120:123]
	v_mfma_f32_16x16x16_bf16 v[108:111], v[94:95], v[32:33], v[108:111]
	v_mfma_f32_16x16x16_bf16 v[124:127], v[94:95], v[64:65], v[124:127]
	s_waitcnt lgkmcnt(0)
	s_add_i32 s93, s79, 0xffffff00
	s_mov_b32 m0, s15
	v_add_u32_e32 v164, s93, v162
	v_med3_i32 v164, v164, 0, s40
	v_lshl_or_b32 v164, v164, 7, v220
	global_load_lds_dwordx4 v164, s[20:21]
	s_add_i32 m0, s15, 0x400
	v_add_u32_e32 v165, s93, v163
	v_med3_i32 v165, v165, 0, s40
	v_lshl_or_b32 v165, v165, 7, v221
	global_load_lds_dwordx4 v165, s[20:21]
	v_mfma_f32_16x16x16_bf16 v[112:115], v[202:203], v[68:69], v[112:115]
	v_mfma_f32_16x16x16_bf16 v[116:119], v[204:205], v[68:69], v[116:119]
	v_mfma_f32_16x16x16_bf16 v[120:123], v[206:207], v[68:69], v[120:123]
	v_mfma_f32_16x16x16_bf16 v[124:127], v[208:209], v[68:69], v[124:127]
	s_waitcnt lgkmcnt(0)
	v_max_f32_e32 v146, v144, v184
	v_sub_f32_e32 v148, v144, v146
	v_sub_f32_e32 v150, v184, v146
	v_exp_f32_e32 v148, v148
	v_exp_f32_e32 v150, v150
	v_mov_b32_e32 v184, v146
	v_mul_f32_e32 v185, v185, v150
	v_fmac_f32_e32 v185, v145, v148
	v_pk_mul_f32 v[96:97], v[150:151], v[96:97] op_sel_hi:[0,1]
	v_pk_mul_f32 v[98:99], v[150:151], v[98:99] op_sel_hi:[0,1]
	v_pk_mul_f32 v[100:101], v[150:151], v[100:101] op_sel_hi:[0,1]
	v_pk_mul_f32 v[102:103], v[150:151], v[102:103] op_sel_hi:[0,1]
	v_pk_mul_f32 v[104:105], v[150:151], v[104:105] op_sel_hi:[0,1]
	v_pk_mul_f32 v[106:107], v[150:151], v[106:107] op_sel_hi:[0,1]
	v_pk_mul_f32 v[108:109], v[150:151], v[108:109] op_sel_hi:[0,1]
	v_pk_mul_f32 v[110:111], v[150:151], v[110:111] op_sel_hi:[0,1]
	v_pk_fma_f32 v[96:97], v[148:149], v[128:129], v[96:97] op_sel_hi:[0,1,1]
	v_pk_fma_f32 v[98:99], v[148:149], v[130:131], v[98:99] op_sel_hi:[0,1,1]
	v_pk_fma_f32 v[100:101], v[148:149], v[132:133], v[100:101] op_sel_hi:[0,1,1]
	v_pk_fma_f32 v[102:103], v[148:149], v[134:135], v[102:103] op_sel_hi:[0,1,1]
	v_pk_fma_f32 v[104:105], v[148:149], v[136:137], v[104:105] op_sel_hi:[0,1,1]
	v_pk_fma_f32 v[106:107], v[148:149], v[138:139], v[106:107] op_sel_hi:[0,1,1]
	v_pk_fma_f32 v[108:109], v[148:149], v[140:141], v[108:109] op_sel_hi:[0,1,1]
	v_pk_fma_f32 v[110:111], v[148:149], v[142:143], v[110:111] op_sel_hi:[0,1,1]
	s_and_saveexec_b64 s[80:81], s[74:75]
	ds_write_b64 v194, v[184:185]
	s_mov_b64 exec, s[80:81]
	ds_write_b128 v190, v[96:99]
	ds_write_b128 v191, v[100:103]
	ds_write_b128 v192, v[104:107]
	ds_write_b128 v193, v[108:111]
	s_waitcnt lgkmcnt(0)
	v_max_f32_e32 v146, v182, v186
	v_sub_f32_e32 v148, v182, v146
	v_sub_f32_e32 v150, v186, v146
	v_exp_f32_e32 v148, v148
	v_exp_f32_e32 v150, v150
	v_mov_b32_e32 v186, v146
	v_mul_f32_e32 v187, v187, v150
	v_fmac_f32_e32 v187, v183, v148
	v_pk_mul_f32 v[112:113], v[150:151], v[112:113] op_sel_hi:[0,1]
	v_pk_mul_f32 v[114:115], v[150:151], v[114:115] op_sel_hi:[0,1]
	v_pk_mul_f32 v[116:117], v[150:151], v[116:117] op_sel_hi:[0,1]
	v_pk_mul_f32 v[118:119], v[150:151], v[118:119] op_sel_hi:[0,1]
	v_pk_mul_f32 v[120:121], v[150:151], v[120:121] op_sel_hi:[0,1]
	v_pk_mul_f32 v[122:123], v[150:151], v[122:123] op_sel_hi:[0,1]
	v_pk_mul_f32 v[124:125], v[150:151], v[124:125] op_sel_hi:[0,1]
	v_pk_mul_f32 v[126:127], v[150:151], v[126:127] op_sel_hi:[0,1]
	v_pk_fma_f32 v[112:113], v[148:149], v[166:167], v[112:113] op_sel_hi:[0,1,1]
	v_pk_fma_f32 v[114:115], v[148:149], v[168:169], v[114:115] op_sel_hi:[0,1,1]
	v_pk_fma_f32 v[116:117], v[148:149], v[170:171], v[116:117] op_sel_hi:[0,1,1]
	v_pk_fma_f32 v[118:119], v[148:149], v[172:173], v[118:119] op_sel_hi:[0,1,1]
	v_pk_fma_f32 v[120:121], v[148:149], v[174:175], v[120:121] op_sel_hi:[0,1,1]
	v_pk_fma_f32 v[122:123], v[148:149], v[176:177], v[122:123] op_sel_hi:[0,1,1]
	v_pk_fma_f32 v[124:125], v[148:149], v[178:179], v[124:125] op_sel_hi:[0,1,1]
	v_pk_fma_f32 v[126:127], v[148:149], v[180:181], v[126:127] op_sel_hi:[0,1,1]
	s_and_saveexec_b64 s[80:81], s[74:75]
	ds_write_b64 v199, v[186:187]
	s_mov_b64 exec, s[80:81]
	ds_write_b128 v195, v[112:115]
	ds_write_b128 v196, v[116:119]
	ds_write_b128 v197, v[120:123]
	ds_write_b128 v198, v[124:127]
	s_waitcnt lgkmcnt(0)
	s_barrier
	s_add_i32 s76, s38, s84
	s_add_i32 s79, s39, s82
	v_lshlrev_b32_e32 v231, 4, v218
	v_add_u32_e32 v232, 8, v218
	v_lshlrev_b32_e32 v232, 4, v232
	v_lshlrev_b32_e32 v162, 0, v218
	v_add_u32_e32 v163, 8, v218
	v_lshlrev_b32_e32 v163, 0, v163
	s_add_i32 s8, s38, s85
	s_waitcnt vmcnt(8)
	v_add_u32_e32 v154, s16, v223
	v_add_u32_e32 v155, s16, v224
	ds_read_b128 v[72:75], v154
	ds_read_b128 v[76:79], v155
	s_waitcnt lgkmcnt(0)
	s_add_i32 s93, s76, 0
	s_mov_b32 m0, s16
	v_add_u32_e32 v164, s93, v231
	v_med3_i32 v164, v164, 0, s40
	v_lshl_or_b32 v164, v164, 7, v220
	global_load_lds_dwordx4 v164, s[20:21]
	s_add_i32 m0, s16, 0x400
	v_add_u32_e32 v165, s93, v232
	v_med3_i32 v165, v165, 0, s40
	v_lshl_or_b32 v165, v165, 7, v221
	global_load_lds_dwordx4 v165, s[20:21]
	s_waitcnt vmcnt(8)
	v_add_u32_e32 v154, s12, v223
	v_add_u32_e32 v155, s12, v224
	ds_read_b128 v[202:205], v154
	ds_read_b128 v[206:209], v155
	s_waitcnt lgkmcnt(0)
	s_add_i32 s93, s76, 0x100
	s_mov_b32 m0, s12
	v_add_u32_e32 v164, s93, v231
	v_med3_i32 v164, v164, 0, s40
	v_lshl_or_b32 v164, v164, 7, v220
	global_load_lds_dwordx4 v164, s[20:21]
	s_add_i32 m0, s12, 0x400
	v_add_u32_e32 v165, s93, v232
	v_med3_i32 v165, v165, 0, s40
	v_lshl_or_b32 v165, v165, 7, v221
	global_load_lds_dwordx4 v165, s[20:21]
	s_waitcnt vmcnt(8)
	v_add_u32_e32 v154, s13, v223
	v_add_u32_e32 v155, s13, v224
	ds_read_b128 v[88:91], v154
	ds_read_b128 v[92:95], v155
	v_mfma_f32_16x16x32_bf16 v[0:3], v[202:205], v[72:75], 0
	v_mfma_f32_16x16x32_bf16 v[0:3], v[206:209], v[76:79], v[0:3]
	s_waitcnt lgkmcnt(0)
	s_add_i32 s93, s76, 0x200
	s_mov_b32 m0, s13
	v_add_u32_e32 v164, s93, v231
	v_med3_i32 v164, v164, 0, s40
	v_lshl_or_b32 v164, v164, 7, v220
	global_load_lds_dwordx4 v164, s[20:21]
	s_add_i32 m0, s13, 0x400
	v_add_u32_e32 v165, s93, v232
	v_med3_i32 v165, v165, 0, s40
	v_lshl_or_b32 v165, v165, 7, v221
	global_load_lds_dwordx4 v165, s[20:21]
	s_waitcnt vmcnt(8)
	v_add_u32_e32 v154, s14, v223
	v_add_u32_e32 v155, s14, v224
	ds_read_b128 v[202:205], v154
	ds_read_b128 v[206:209], v155
	v_mfma_f32_16x16x32_bf16 v[4:7], v[88:91], v[72:75], 0
	v_mfma_f32_16x16x32_bf16 v[4:7], v[92:95], v[76:79], v[4:7]
	s_waitcnt lgkmcnt(0)
	s_add_i32 s93, s76, 0x300
	s_mov_b32 m0, s14
	v_add_u32_e32 v164, s93, v231
	v_med3_i32 v164, v164, 0, s40
	v_lshl_or_b32 v164, v164, 7, v220
	global_load_lds_dwordx4 v164, s[20:21]
	s_add_i32 m0, s14, 0x400
	v_add_u32_e32 v165, s93, v232
	v_med3_i32 v165, v165, 0, s40
	v_lshl_or_b32 v165, v165, 7, v221
	global_load_lds_dwordx4 v165, s[20:21]
	s_waitcnt vmcnt(8)
	v_add_u32_e32 v154, s15, v223
	v_add_u32_e32 v155, s15, v224
	ds_read_b128 v[88:91], v154
	ds_read_b128 v[92:95], v155
	v_mfma_f32_16x16x32_bf16 v[8:11], v[202:205], v[72:75], 0
	v_mfma_f32_16x16x32_bf16 v[8:11], v[206:209], v[76:79], v[8:11]
	s_waitcnt lgkmcnt(0)
	s_add_i32 s93, s76, 0x400
	s_mov_b32 m0, s15
	v_add_u32_e32 v164, s93, v231
	v_med3_i32 v164, v164, 0, s40
	v_lshl_or_b32 v164, v164, 7, v220
	global_load_lds_dwordx4 v164, s[20:21]
	s_add_i32 m0, s15, 0x400
	v_add_u32_e32 v165, s93, v232
	v_med3_i32 v165, v165, 0, s40
	v_lshl_or_b32 v165, v165, 7, v221
	global_load_lds_dwordx4 v165, s[20:21]
	s_waitcnt vmcnt(8)
	v_add_u32_e32 v154, s16, v223
	v_add_u32_e32 v155, s16, v224
	ds_read_b128 v[202:205], v154
	ds_read_b128 v[206:209], v155
	v_mfma_f32_16x16x32_bf16 v[12:15], v[88:91], v[72:75], 0
	v_mfma_f32_16x16x32_bf16 v[12:15], v[92:95], v[76:79], v[12:15]
	s_waitcnt lgkmcnt(0)
	s_add_i32 s93, s8, 0
	s_mov_b32 m0, s16
	v_add_u32_e32 v164, s93, v231
	v_lshl_or_b32 v164, v164, 7, v220
	global_load_lds_dwordx4 v164, s[18:19]
	s_add_i32 m0, s16, 0x400
	v_add_u32_e32 v165, s93, v232
	v_lshl_or_b32 v165, v165, 7, v221
	global_load_lds_dwordx4 v165, s[18:19]
	s_waitcnt vmcnt(8)
	v_add_u32_e32 v154, s12, v223
	v_add_u32_e32 v155, s12, v224
	ds_read_b128 v[88:91], v154
	ds_read_b128 v[92:95], v155
	v_mfma_f32_16x16x32_bf16 v[16:19], v[202:205], v[72:75], 0
	v_mfma_f32_16x16x32_bf16 v[16:19], v[206:209], v[76:79], v[16:19]
	s_waitcnt lgkmcnt(0)
	s_add_i32 s93, s8, 0xfffffc00
	s_mov_b32 m0, s12
	v_add_u32_e32 v164, s93, v231
	v_med3_i32 v164, v164, 0, s40
	v_lshl_or_b32 v164, v164, 7, v220
	global_load_lds_dwordx4 v164, s[20:21]
	s_add_i32 m0, s12, 0x400
	v_add_u32_e32 v165, s93, v232
	v_med3_i32 v165, v165, 0, s40
	v_lshl_or_b32 v165, v165, 7, v221
	global_load_lds_dwordx4 v165, s[20:21]
	s_waitcnt vmcnt(8)
	v_add_u32_e32 v154, s13, v223
	v_add_u32_e32 v155, s13, v224
	ds_read_b128 v[202:205], v154
	ds_read_b128 v[206:209], v155
	v_mfma_f32_16x16x32_bf16 v[20:23], v[88:91], v[72:75], 0
	v_mfma_f32_16x16x32_bf16 v[20:23], v[92:95], v[76:79], v[20:23]
	s_waitcnt lgkmcnt(0)
	s_add_i32 s93, s8, 0xfffffd00
	s_mov_b32 m0, s13
	v_add_u32_e32 v164, s93, v231
	v_med3_i32 v164, v164, 0, s40
	v_lshl_or_b32 v164, v164, 7, v220
	global_load_lds_dwordx4 v164, s[20:21]
	s_add_i32 m0, s13, 0x400
	v_add_u32_e32 v165, s93, v232
	v_med3_i32 v165, v165, 0, s40
	v_lshl_or_b32 v165, v165, 7, v221
	global_load_lds_dwordx4 v165, s[20:21]
	s_waitcnt vmcnt(8)
	v_add_u32_e32 v154, s14, v223
	v_add_u32_e32 v155, s14, v224
	ds_read_b128 v[88:91], v154
	ds_read_b128 v[92:95], v155
	v_mfma_f32_16x16x32_bf16 v[24:27], v[202:205], v[72:75], 0
	v_mfma_f32_16x16x32_bf16 v[24:27], v[206:209], v[76:79], v[24:27]
	s_waitcnt lgkmcnt(0)
	s_add_i32 s93, s8, 0xfffffe00
	s_mov_b32 m0, s14
	v_add_u32_e32 v164, s93, v231
	v_med3_i32 v164, v164, 0, s40
	v_lshl_or_b32 v164, v164, 7, v220
	global_load_lds_dwordx4 v164, s[20:21]
	s_add_i32 m0, s14, 0x400
	v_add_u32_e32 v165, s93, v232
	v_med3_i32 v165, v165, 0, s40
	v_lshl_or_b32 v165, v165, 7, v221
	global_load_lds_dwordx4 v165, s[20:21]
	s_waitcnt vmcnt(8)
	v_add_u32_e32 v154, s15, v223
	v_add_u32_e32 v155, s15, v224
	ds_read_b128 v[202:205], v154
	ds_read_b128 v[206:209], v155
	v_mfma_f32_16x16x32_bf16 v[28:31], v[88:91], v[72:75], 0
	v_mfma_f32_16x16x32_bf16 v[28:31], v[92:95], v[76:79], v[28:31]
	s_waitcnt lgkmcnt(0)
	s_add_i32 s93, s8, 0xffffff00
	s_mov_b32 m0, s15
	v_add_u32_e32 v164, s93, v231
	v_med3_i32 v164, v164, 0, s40
	v_lshl_or_b32 v164, v164, 7, v220
	global_load_lds_dwordx4 v164, s[20:21]
	s_add_i32 m0, s15, 0x400
	v_add_u32_e32 v165, s93, v232
	v_med3_i32 v165, v165, 0, s40
	v_lshl_or_b32 v165, v165, 7, v221
	global_load_lds_dwordx4 v165, s[20:21]
	s_waitcnt vmcnt(8)
	v_add_u32_e32 v154, s16, v223
	v_add_u32_e32 v155, s16, v224
	ds_read_b128 v[80:83], v154
	ds_read_b128 v[84:87], v155
	v_mfma_f32_16x16x32_bf16 v[32:35], v[202:205], v[72:75], 0
	v_mfma_f32_16x16x32_bf16 v[32:35], v[206:209], v[76:79], v[32:35]
	s_waitcnt lgkmcnt(0)
	s_add_i32 s93, s8, 0
	s_mov_b32 m0, s16
	v_add_u32_e32 v164, s93, v231
	v_med3_i32 v164, v164, 0, s40
	v_lshl_or_b32 v164, v164, 7, v220
	global_load_lds_dwordx4 v164, s[20:21]
	s_add_i32 m0, s16, 0x400
	v_add_u32_e32 v165, s93, v232
	v_med3_i32 v165, v165, 0, s40
	v_lshl_or_b32 v165, v165, 7, v221
	global_load_lds_dwordx4 v165, s[20:21]
	s_waitcnt vmcnt(8)
	v_add_u32_e32 v154, s12, v223
	v_add_u32_e32 v155, s12, v224
	ds_read_b128 v[202:205], v154
	ds_read_b128 v[206:209], v155
	v_mov_b32_e32 v188, s84
	v_lshl_add_u32 v188, v216, 4, v188
	v_lshrrev_b32_e32 v146, 4, v188
	v_xor_b32_e32 v146, v146, v188
	v_and_b32_e32 v146, 15, v146
	v_lshlrev_b32_e32 v147, 8, v188
	v_or_b32_e32 v148, 0, v217
	v_xor_b32_e32 v148, v148, v146
	v_lshl_add_u32 v190, v148, 4, v147
	v_or_b32_e32 v148, 4, v217
	v_xor_b32_e32 v148, v148, v146
	v_lshl_add_u32 v191, v148, 4, v147
	v_or_b32_e32 v148, 8, v217
	v_xor_b32_e32 v148, v148, v146
	v_lshl_add_u32 v192, v148, 4, v147
	v_or_b32_e32 v148, 12, v217
	v_xor_b32_e32 v148, v148, v146
	v_lshl_add_u32 v193, v148, 4, v147
	v_lshlrev_b32_e32 v194, 3, v188
	v_add_u32_e32 v194, 0x10000, v194
	ds_read_b64 v[144:145], v194
	ds_read_b128 v[128:131], v190
	ds_read_b128 v[132:135], v191
	ds_read_b128 v[136:139], v192
	ds_read_b128 v[140:143], v193
	s_ashr_i32 s77, s76, 4
	s_sub_i32 s77, 64, s77
	s_sub_i32 s78, s40, s76
	s_waitcnt lgkmcnt(0)
	s_add_i32 s93, s8, 0x100
	s_mov_b32 m0, s12
	v_add_u32_e32 v164, s93, v231
	v_med3_i32 v164, v164, 0, s40
	v_lshl_or_b32 v164, v164, 7, v220
	global_load_lds_dwordx4 v164, s[20:21]
	s_add_i32 m0, s12, 0x400
	v_add_u32_e32 v165, s93, v232
	v_med3_i32 v165, v165, 0, s40
	v_lshl_or_b32 v165, v165, 7, v221
	global_load_lds_dwordx4 v165, s[20:21]
	s_waitcnt vmcnt(8)
	v_add_u32_e32 v154, s13, v223
	v_add_u32_e32 v155, s13, v224
	ds_read_b128 v[88:91], v154
	ds_read_b128 v[92:95], v155
	v_mfma_f32_16x16x32_bf16 v[36:39], v[202:205], v[80:83], 0
	v_mfma_f32_16x16x32_bf16 v[36:39], v[206:209], v[84:87], v[36:39]
	s_ashr_i32 s78, s78, 4
	s_add_i32 s78, s78, 64
	v_cndmask_b32_e64 v0, v0, v230, s[52:53]
	v_cndmask_b32_e64 v32, v32, v230, s[62:63]
	v_cndmask_b32_e64 v1, v1, v230, s[56:57]
	v_cndmask_b32_e64 v33, v33, v230, s[64:65]
	v_cndmask_b32_e64 v2, v2, v230, s[58:59]
	v_cndmask_b32_e64 v34, v34, v230, s[70:71]
	v_cndmask_b32_e64 v3, v3, v230, s[60:61]
	v_cndmask_b32_e64 v35, v35, v230, s[72:73]
	v_sub_u32_e32 v200, s77, v229
	s_sub_i32 s91, s78, s77
	v_sub_u32_e32 v150, 0, v200
	v_sub_u32_e32 v151, 1, v200
	v_sub_u32_e32 v152, 2, v200
	v_sub_u32_e32 v153, 3, v200
	v_cmp_lt_u32_e64 s[94:95], s91, v150
	v_cmp_lt_u32_e64 s[86:87], s91, v151
	v_cmp_lt_u32_e64 s[0:1], s91, v152
	v_cmp_lt_u32_e64 s[2:3], s91, v153
	v_cndmask_b32_e64 v0, v0, v230, s[94:95]
	v_cndmask_b32_e64 v1, v1, v230, s[86:87]
	v_cndmask_b32_e64 v2, v2, v230, s[0:1]
	v_cndmask_b32_e64 v3, v3, v230, s[2:3]
	v_sub_u32_e32 v150, 16, v200
	v_sub_u32_e32 v151, 17, v200
	v_sub_u32_e32 v152, 18, v200
	v_sub_u32_e32 v153, 19, v200
	s_waitcnt lgkmcnt(0)
	s_add_i32 s93, s8, 0x200
	s_mov_b32 m0, s13
	v_add_u32_e32 v164, s93, v231
	v_med3_i32 v164, v164, 0, s40
	v_lshl_or_b32 v164, v164, 7, v220
	global_load_lds_dwordx4 v164, s[20:21]
	s_add_i32 m0, s13, 0x400
	v_add_u32_e32 v165, s93, v232
	v_med3_i32 v165, v165, 0, s40
	v_lshl_or_b32 v165, v165, 7, v221
	global_load_lds_dwordx4 v165, s[20:21]
	s_waitcnt vmcnt(8)
	v_add_u32_e32 v154, s14, v223
	v_add_u32_e32 v155, s14, v224
	ds_read_b128 v[202:205], v154
	ds_read_b128 v[206:209], v155
	v_mfma_f32_16x16x32_bf16 v[40:43], v[88:91], v[80:83], 0
	v_mfma_f32_16x16x32_bf16 v[40:43], v[92:95], v[84:87], v[40:43]
	v_cmp_lt_u32_e64 s[94:95], s91, v150
	v_cmp_lt_u32_e64 s[86:87], s91, v151
	v_cmp_lt_u32_e64 s[0:1], s91, v152
	v_cmp_lt_u32_e64 s[2:3], s91, v153
	v_cndmask_b32_e64 v4, v4, v230, s[94:95]
	v_cndmask_b32_e64 v5, v5, v230, s[86:87]
	v_cndmask_b32_e64 v6, v6, v230, s[0:1]
	v_cndmask_b32_e64 v7, v7, v230, s[2:3]
	v_sub_u32_e32 v150, 32, v200
	v_sub_u32_e32 v151, 33, v200
	v_sub_u32_e32 v152, 34, v200
	v_sub_u32_e32 v153, 35, v200
	v_cmp_lt_u32_e64 s[94:95], s91, v150
	v_cmp_lt_u32_e64 s[86:87], s91, v151
	v_cmp_lt_u32_e64 s[0:1], s91, v152
	v_cmp_lt_u32_e64 s[2:3], s91, v153
	v_cndmask_b32_e64 v8, v8, v230, s[94:95]
	v_cndmask_b32_e64 v9, v9, v230, s[86:87]
	v_cndmask_b32_e64 v10, v10, v230, s[0:1]
	v_cndmask_b32_e64 v11, v11, v230, s[2:3]
	v_sub_u32_e32 v150, 48, v200
	v_sub_u32_e32 v151, 49, v200
	v_sub_u32_e32 v152, 50, v200
	v_sub_u32_e32 v153, 51, v200
	v_cmp_lt_u32_e64 s[94:95], s91, v150
	v_cmp_lt_u32_e64 s[86:87], s91, v151
	v_cmp_lt_u32_e64 s[0:1], s91, v152
	v_cmp_lt_u32_e64 s[2:3], s91, v153
	s_waitcnt lgkmcnt(0)
	s_add_i32 s93, s8, 0x300
	s_mov_b32 m0, s14
	v_add_u32_e32 v164, s93, v231
	v_med3_i32 v164, v164, 0, s40
	v_lshl_or_b32 v164, v164, 7, v220
	global_load_lds_dwordx4 v164, s[20:21]
	s_add_i32 m0, s14, 0x400
	v_add_u32_e32 v165, s93, v232
	v_med3_i32 v165, v165, 0, s40
	v_lshl_or_b32 v165, v165, 7, v221
	global_load_lds_dwordx4 v165, s[20:21]
	s_waitcnt vmcnt(8)
	v_add_u32_e32 v154, s15, v223
	v_add_u32_e32 v155, s15, v224
	ds_read_b128 v[88:91], v154
	ds_read_b128 v[92:95], v155
	v_mfma_f32_16x16x32_bf16 v[44:47], v[202:205], v[80:83], 0
	v_mfma_f32_16x16x32_bf16 v[44:47], v[206:209], v[84:87], v[44:47]
	v_cndmask_b32_e64 v12, v12, v230, s[94:95]
	v_cndmask_b32_e64 v13, v13, v230, s[86:87]
	v_cndmask_b32_e64 v14, v14, v230, s[0:1]
	v_cndmask_b32_e64 v15, v15, v230, s[2:3]
	v_sub_u32_e32 v150, 64, v200
	v_sub_u32_e32 v151, 0x41, v200
	v_sub_u32_e32 v152, 0x42, v200
	v_sub_u32_e32 v153, 0x43, v200
	v_cmp_lt_u32_e64 s[94:95], s91, v150
	v_cmp_lt_u32_e64 s[86:87], s91, v151
	v_cmp_lt_u32_e64 s[0:1], s91, v152
	v_cmp_lt_u32_e64 s[2:3], s91, v153
	v_cndmask_b32_e64 v16, v16, v230, s[94:95]
	v_cndmask_b32_e64 v17, v17, v230, s[86:87]
	v_cndmask_b32_e64 v18, v18, v230, s[0:1]
	v_cndmask_b32_e64 v19, v19, v230, s[2:3]
	v_sub_u32_e32 v150, 0x50, v200
	v_sub_u32_e32 v151, 0x51, v200
	v_sub_u32_e32 v152, 0x52, v200
	v_sub_u32_e32 v153, 0x53, v200
	v_cmp_lt_u32_e64 s[94:95], s91, v150
	v_cmp_lt_u32_e64 s[86:87], s91, v151
	v_cmp_lt_u32_e64 s[0:1], s91, v152
	v_cmp_lt_u32_e64 s[2:3], s91, v153
	v_cndmask_b32_e64 v20, v20, v230, s[94:95]
	v_cndmask_b32_e64 v21, v21, v230, s[86:87]
	v_cndmask_b32_e64 v22, v22, v230, s[0:1]
	v_cndmask_b32_e64 v23, v23, v230, s[2:3]
	s_waitcnt lgkmcnt(0)
	s_add_i32 s93, s8, 0x400
	s_mov_b32 m0, s15
	v_add_u32_e32 v164, s93, v231
	v_med3_i32 v164, v164, 0, s40
	v_lshl_or_b32 v164, v164, 7, v220
	global_load_lds_dwordx4 v164, s[20:21]
	s_add_i32 m0, s15, 0x400
	v_add_u32_e32 v165, s93, v232
	v_med3_i32 v165, v165, 0, s40
	v_lshl_or_b32 v165, v165, 7, v221
	global_load_lds_dwordx4 v165, s[20:21]
	s_waitcnt vmcnt(8)
	v_add_u32_e32 v154, s16, v223
	v_add_u32_e32 v155, s16, v224
	ds_read_b128 v[202:205], v154
	ds_read_b128 v[206:209], v155
	v_mfma_f32_16x16x32_bf16 v[48:51], v[88:91], v[80:83], 0
	v_mfma_f32_16x16x32_bf16 v[48:51], v[92:95], v[84:87], v[48:51]
	v_sub_u32_e32 v150, 0x60, v200
	v_sub_u32_e32 v151, 0x61, v200
	v_sub_u32_e32 v152, 0x62, v200
	v_sub_u32_e32 v153, 0x63, v200
	v_cmp_lt_u32_e64 s[94:95], s91, v150
	v_cmp_lt_u32_e64 s[86:87], s91, v151
	v_cmp_lt_u32_e64 s[0:1], s91, v152
	v_cmp_lt_u32_e64 s[2:3], s91, v153
	v_cndmask_b32_e64 v24, v24, v230, s[94:95]
	v_cndmask_b32_e64 v25, v25, v230, s[86:87]
	v_cndmask_b32_e64 v26, v26, v230, s[0:1]
	v_cndmask_b32_e64 v27, v27, v230, s[2:3]
	v_sub_u32_e32 v150, 0x70, v200
	v_sub_u32_e32 v151, 0x71, v200
	v_sub_u32_e32 v152, 0x72, v200
	v_sub_u32_e32 v153, 0x73, v200
	v_cmp_lt_u32_e64 s[94:95], s91, v150
	v_cmp_lt_u32_e64 s[86:87], s91, v151
	v_cmp_lt_u32_e64 s[0:1], s91, v152
	v_cmp_lt_u32_e64 s[2:3], s91, v153
	v_cndmask_b32_e64 v28, v28, v230, s[94:95]
	v_cndmask_b32_e64 v29, v29, v230, s[86:87]
	v_cndmask_b32_e64 v30, v30, v230, s[0:1]
	v_cndmask_b32_e64 v31, v31, v230, s[2:3]
	v_sub_u32_e32 v150, 0x80, v200
	v_sub_u32_e32 v151, 0x81, v200
	v_sub_u32_e32 v152, 0x82, v200
	v_sub_u32_e32 v153, 0x83, v200
	s_waitcnt lgkmcnt(0)
	s_add_i32 s93, s76, 0xfffffc00
	s_mov_b32 m0, s16
	v_add_u32_e32 v164, s93, v231
	v_med3_i32 v164, v164, 0, s40
	v_lshl_or_b32 v164, v164, 7, v222
	global_load_lds_dwordx4 v164, s[24:25]
	s_add_i32 m0, s16, 0x400
	v_add_u32_e32 v165, s93, v232
	v_med3_i32 v165, v165, 0, s40
	v_lshl_or_b32 v165, v165, 7, v222
	global_load_lds_dwordx4 v165, s[24:25]
	s_waitcnt vmcnt(8)
	v_add_u32_e32 v154, s12, v223
	v_add_u32_e32 v155, s12, v224
	ds_read_b128 v[88:91], v154
	ds_read_b128 v[92:95], v155
	v_mfma_f32_16x16x32_bf16 v[52:55], v[202:205], v[80:83], 0
	v_mfma_f32_16x16x32_bf16 v[52:55], v[206:209], v[84:87], v[52:55]
	v_cmp_lt_u32_e64 s[94:95], s91, v150
	v_cmp_lt_u32_e64 s[86:87], s91, v151
	v_cmp_lt_u32_e64 s[0:1], s91, v152
	v_cmp_lt_u32_e64 s[2:3], s91, v153
	v_cndmask_b32_e64 v32, v32, v230, s[94:95]
	v_cndmask_b32_e64 v33, v33, v230, s[86:87]
	v_cndmask_b32_e64 v34, v34, v230, s[0:1]
	v_cndmask_b32_e64 v35, v35, v230, s[2:3]
	v_max3_f32 v184, v0, v1, v2
	v_max3_f32 v184, v184, v3, v4
	v_max3_f32 v184, v184, v5, v6
	v_max3_f32 v184, v184, v7, v8
	v_max3_f32 v184, v184, v9, v10
	v_max3_f32 v184, v184, v11, v12
	v_max3_f32 v184, v184, v13, v14
	v_max3_f32 v184, v184, v15, v16
	v_max3_f32 v184, v184, v17, v18
	v_max3_f32 v184, v184, v19, v20
	v_max3_f32 v184, v184, v21, v22
	v_max3_f32 v184, v184, v23, v24
	v_max3_f32 v184, v184, v25, v26
	v_max3_f32 v184, v184, v27, v28
	v_max3_f32 v184, v184, v29, v30
	v_max3_f32 v184, v184, v31, v32
	v_max3_f32 v184, v184, v33, v34
	v_max_f32_e32 v184, v184, v35
	v_mov_b32_e32 v146, v184
	s_nop 1
	v_permlane16_swap_b32_e32 v184, v146
	s_waitcnt lgkmcnt(0)
	s_add_i32 s93, s76, 0xfffffd00
	s_mov_b32 m0, s12
	v_add_u32_e32 v164, s93, v231
	v_med3_i32 v164, v164, 0, s40
	v_lshl_or_b32 v164, v164, 7, v222
	global_load_lds_dwordx4 v164, s[24:25]
	s_add_i32 m0, s12, 0x400
	v_add_u32_e32 v165, s93, v232
	v_med3_i32 v165, v165, 0, s40
	v_lshl_or_b32 v165, v165, 7, v222
	global_load_lds_dwordx4 v165, s[24:25]
	s_waitcnt vmcnt(8)
	v_add_u32_e32 v154, s13, v223
	v_add_u32_e32 v155, s13, v224
	ds_read_b128 v[202:205], v154
	ds_read_b128 v[206:209], v155
	v_mfma_f32_16x16x32_bf16 v[56:59], v[88:91], v[80:83], 0
	v_mfma_f32_16x16x32_bf16 v[56:59], v[92:95], v[84:87], v[56:59]
	v_max_f32_e32 v184, v184, v146
	v_mov_b32_e32 v146, v184
	s_nop 1
	v_permlane32_swap_b32_e32 v184, v146
	v_max_f32_e32 v184, v184, v146
	v_pk_add_f32 v[0:1], v[0:1], v[184:185] op_sel_hi:[1,0] neg_lo:[0,1] neg_hi:[0,1]
	v_pk_add_f32 v[2:3], v[2:3], v[184:185] op_sel_hi:[1,0] neg_lo:[0,1] neg_hi:[0,1]
	v_pk_add_f32 v[4:5], v[4:5], v[184:185] op_sel_hi:[1,0] neg_lo:[0,1] neg_hi:[0,1]
	v_pk_add_f32 v[6:7], v[6:7], v[184:185] op_sel_hi:[1,0] neg_lo:[0,1] neg_hi:[0,1]
	v_exp_f32_e32 v0, v0
	v_exp_f32_e32 v1, v1
	v_exp_f32_e32 v2, v2
	v_exp_f32_e32 v3, v3
	v_pk_add_f32 v[8:9], v[8:9], v[184:185] op_sel_hi:[1,0] neg_lo:[0,1] neg_hi:[0,1]
	v_pk_add_f32 v[10:11], v[10:11], v[184:185] op_sel_hi:[1,0] neg_lo:[0,1] neg_hi:[0,1]
	v_exp_f32_e32 v4, v4
	v_exp_f32_e32 v5, v5
	v_exp_f32_e32 v6, v6
	v_exp_f32_e32 v7, v7
	v_pk_add_f32 v[12:13], v[12:13], v[184:185] op_sel_hi:[1,0] neg_lo:[0,1] neg_hi:[0,1]
	v_pk_add_f32 v[14:15], v[14:15], v[184:185] op_sel_hi:[1,0] neg_lo:[0,1] neg_hi:[0,1]
	v_exp_f32_e32 v8, v8
	v_exp_f32_e32 v9, v9
	v_exp_f32_e32 v10, v10
	v_exp_f32_e32 v11, v11
	v_pk_add_f32 v[16:17], v[16:17], v[184:185] op_sel_hi:[1,0] neg_lo:[0,1] neg_hi:[0,1]
	v_pk_add_f32 v[18:19], v[18:19], v[184:185] op_sel_hi:[1,0] neg_lo:[0,1] neg_hi:[0,1]
	v_exp_f32_e32 v12, v12
	v_exp_f32_e32 v13, v13
	s_waitcnt lgkmcnt(0)
	s_add_i32 s93, s76, 0xfffffe00
	s_mov_b32 m0, s13
	v_add_u32_e32 v164, s93, v231
	v_med3_i32 v164, v164, 0, s40
	v_lshl_or_b32 v164, v164, 7, v222
	global_load_lds_dwordx4 v164, s[24:25]
	s_add_i32 m0, s13, 0x400
	v_add_u32_e32 v165, s93, v232
	v_med3_i32 v165, v165, 0, s40
	v_lshl_or_b32 v165, v165, 7, v222
	global_load_lds_dwordx4 v165, s[24:25]
	s_waitcnt vmcnt(8)
	v_add_u32_e32 v154, s14, v223
	v_add_u32_e32 v155, s14, v224
	ds_read_b128 v[88:91], v154
	ds_read_b128 v[92:95], v155
	v_mfma_f32_16x16x32_bf16 v[60:63], v[202:205], v[80:83], 0
	v_mfma_f32_16x16x32_bf16 v[60:63], v[206:209], v[84:87], v[60:63]
	v_exp_f32_e32 v14, v14
	v_exp_f32_e32 v15, v15
	v_pk_add_f32 v[20:21], v[20:21], v[184:185] op_sel_hi:[1,0] neg_lo:[0,1] neg_hi:[0,1]
	v_pk_add_f32 v[22:23], v[22:23], v[184:185] op_sel_hi:[1,0] neg_lo:[0,1] neg_hi:[0,1]
	v_exp_f32_e32 v16, v16
	v_exp_f32_e32 v17, v17
	v_exp_f32_e32 v18, v18
	v_exp_f32_e32 v19, v19
	v_pk_add_f32 v[24:25], v[24:25], v[184:185] op_sel_hi:[1,0] neg_lo:[0,1] neg_hi:[0,1]
	v_pk_add_f32 v[26:27], v[26:27], v[184:185] op_sel_hi:[1,0] neg_lo:[0,1] neg_hi:[0,1]
	v_exp_f32_e32 v20, v20
	v_exp_f32_e32 v21, v21
	v_exp_f32_e32 v22, v22
	v_exp_f32_e32 v23, v23
	v_pk_add_f32 v[28:29], v[28:29], v[184:185] op_sel_hi:[1,0] neg_lo:[0,1] neg_hi:[0,1]
	v_pk_add_f32 v[30:31], v[30:31], v[184:185] op_sel_hi:[1,0] neg_lo:[0,1] neg_hi:[0,1]
	v_exp_f32_e32 v24, v24
	v_exp_f32_e32 v25, v25
	v_exp_f32_e32 v26, v26
	v_exp_f32_e32 v27, v27
	v_pk_add_f32 v[32:33], v[32:33], v[184:185] op_sel_hi:[1,0] neg_lo:[0,1] neg_hi:[0,1]
	v_pk_add_f32 v[34:35], v[34:35], v[184:185] op_sel_hi:[1,0] neg_lo:[0,1] neg_hi:[0,1]
	v_exp_f32_e32 v28, v28
	v_exp_f32_e32 v29, v29
	v_exp_f32_e32 v30, v30
	v_exp_f32_e32 v31, v31
	v_exp_f32_e32 v32, v32
	v_exp_f32_e32 v33, v33
	s_waitcnt lgkmcnt(0)
	s_add_i32 s93, s76, 0xffffff00
	s_mov_b32 m0, s14
	v_add_u32_e32 v164, s93, v231
	v_med3_i32 v164, v164, 0, s40
	v_lshl_or_b32 v164, v164, 7, v222
	global_load_lds_dwordx4 v164, s[24:25]
	s_add_i32 m0, s14, 0x400
	v_add_u32_e32 v165, s93, v232
	v_med3_i32 v165, v165, 0, s40
	v_lshl_or_b32 v165, v165, 7, v222
	global_load_lds_dwordx4 v165, s[24:25]
	s_waitcnt vmcnt(8)
	v_add_u32_e32 v154, s15, v223
	v_add_u32_e32 v155, s15, v224
	ds_read_b128 v[202:205], v154
	ds_read_b128 v[206:209], v155
	v_mfma_f32_16x16x32_bf16 v[64:67], v[88:91], v[80:83], 0
	v_mfma_f32_16x16x32_bf16 v[64:67], v[92:95], v[84:87], v[64:67]
	v_exp_f32_e32 v34, v34
	v_exp_f32_e32 v35, v35
	s_nop 0
	v_pk_add_f32 v[146:147], v[0:1], v[2:3]
	v_pk_add_f32 v[148:149], v[4:5], v[6:7]
	v_pk_add_f32 v[146:147], v[146:147], v[8:9]
	v_pk_add_f32 v[148:149], v[148:149], v[10:11]
	v_pk_add_f32 v[146:147], v[146:147], v[12:13]
	v_pk_add_f32 v[148:149], v[148:149], v[14:15]
	v_pk_add_f32 v[146:147], v[146:147], v[16:17]
	v_pk_add_f32 v[148:149], v[148:149], v[18:19]
	v_pk_add_f32 v[146:147], v[146:147], v[20:21]
	v_pk_add_f32 v[148:149], v[148:149], v[22:23]
	v_pk_add_f32 v[146:147], v[146:147], v[24:25]
	v_pk_add_f32 v[148:149], v[148:149], v[26:27]
	v_pk_add_f32 v[146:147], v[146:147], v[28:29]
	v_pk_add_f32 v[148:149], v[148:149], v[30:31]
	v_pk_add_f32 v[146:147], v[146:147], v[32:33]
	v_pk_add_f32 v[148:149], v[148:149], v[34:35]
	s_nop 0
	v_pk_add_f32 v[146:147], v[146:147], v[148:149]
	s_nop 0
	v_add_f32_e32 v185, v146, v147
	v_cvt_pk_bf16_f32 v0, v0, v1
	v_cvt_pk_bf16_f32 v1, v2, v3
	v_cvt_pk_bf16_f32 v4, v4, v5
	v_cvt_pk_bf16_f32 v5, v6, v7
	v_cvt_pk_bf16_f32 v8, v8, v9
	s_waitcnt lgkmcnt(0)
	s_add_i32 s93, s76, 0
	s_mov_b32 m0, s15
	v_add_u32_e32 v164, s93, v231
	v_med3_i32 v164, v164, 0, s40
	v_lshl_or_b32 v164, v164, 7, v222
	global_load_lds_dwordx4 v164, s[24:25]
	s_add_i32 m0, s15, 0x400
	v_add_u32_e32 v165, s93, v232
	v_med3_i32 v165, v165, 0, s40
	v_lshl_or_b32 v165, v165, 7, v222
	global_load_lds_dwordx4 v165, s[24:25]
	s_waitcnt vmcnt(8)
	v_add_u32_e32 v154, s16, v225
	v_add_u32_e32 v155, s16, v226
	v_add_u32_e32 v156, s16, v227
	v_add_u32_e32 v157, s16, v228
	ds_read_b64_tr_b16 v[88:89], v154
	ds_read_b64_tr_b16 v[90:91], v155
	ds_read_b64_tr_b16 v[92:93], v156
	ds_read_b64_tr_b16 v[94:95], v157
	v_mfma_f32_16x16x32_bf16 v[68:71], v[202:205], v[80:83], 0
	v_mfma_f32_16x16x32_bf16 v[68:71], v[206:209], v[84:87], v[68:71]
	v_cvt_pk_bf16_f32 v9, v10, v11
	v_cvt_pk_bf16_f32 v12, v12, v13
	v_cvt_pk_bf16_f32 v13, v14, v15
	v_cvt_pk_bf16_f32 v16, v16, v17
	v_cvt_pk_bf16_f32 v17, v18, v19
	v_cvt_pk_bf16_f32 v20, v20, v21
	v_cvt_pk_bf16_f32 v21, v22, v23
	v_cvt_pk_bf16_f32 v24, v24, v25
	v_cvt_pk_bf16_f32 v25, v26, v27
	v_cvt_pk_bf16_f32 v28, v28, v29
	v_cvt_pk_bf16_f32 v29, v30, v31
	v_cvt_pk_bf16_f32 v32, v32, v33
	v_cvt_pk_bf16_f32 v33, v34, v35
	v_mov_b32_e32 v146, v185
	s_nop 1
	v_permlane16_swap_b32_e32 v185, v146
	v_add_f32_e32 v185, v185, v146
	v_mov_b32_e32 v146, v185
	s_nop 1
	v_permlane32_swap_b32_e32 v185, v146
	v_add_f32_e32 v185, v185, v146
	s_waitcnt lgkmcnt(0)
	s_add_i32 s93, s76, 0x100
	s_mov_b32 m0, s16
	v_add_u32_e32 v164, s93, v231
	v_med3_i32 v164, v164, 0, s40
	v_lshl_or_b32 v164, v164, 7, v222
	global_load_lds_dwordx4 v164, s[24:25]
	s_add_i32 m0, s16, 0x400
	v_add_u32_e32 v165, s93, v232
	v_med3_i32 v165, v165, 0, s40
	v_lshl_or_b32 v165, v165, 7, v222
	global_load_lds_dwordx4 v165, s[24:25]
	s_waitcnt vmcnt(8)
	v_add_u32_e32 v154, s12, v225
	v_add_u32_e32 v155, s12, v226
	v_add_u32_e32 v156, s12, v227
	v_add_u32_e32 v157, s12, v228
	ds_read_b64_tr_b16 v[202:203], v154
	ds_read_b64_tr_b16 v[204:205], v155
	ds_read_b64_tr_b16 v[206:207], v156
	ds_read_b64_tr_b16 v[208:209], v157
	v_mfma_f32_16x16x16_bf16 v[96:99], v[88:89], v[0:1], 0
	v_mfma_f32_16x16x16_bf16 v[100:103], v[90:91], v[0:1], 0
	v_mfma_f32_16x16x16_bf16 v[104:107], v[92:93], v[0:1], 0
	v_mfma_f32_16x16x16_bf16 v[108:111], v[94:95], v[0:1], 0
	v_mov_b32_e32 v189, s85
	v_lshl_add_u32 v189, v216, 4, v189
	v_lshrrev_b32_e32 v146, 4, v189
	v_xor_b32_e32 v146, v146, v189
	v_and_b32_e32 v146, 15, v146
	v_lshlrev_b32_e32 v147, 8, v189
	v_or_b32_e32 v148, 0, v217
	v_xor_b32_e32 v148, v148, v146
	v_lshl_add_u32 v195, v148, 4, v147
	v_or_b32_e32 v148, 4, v217
	v_xor_b32_e32 v148, v148, v146
	v_lshl_add_u32 v196, v148, 4, v147
	v_or_b32_e32 v148, 8, v217
	v_xor_b32_e32 v148, v148, v146
	v_lshl_add_u32 v197, v148, 4, v147
	v_or_b32_e32 v148, 12, v217
	v_xor_b32_e32 v148, v148, v146
	v_lshl_add_u32 v198, v148, 4, v147
	v_lshlrev_b32_e32 v199, 3, v189
	v_add_u32_e32 v199, 0x10000, v199
	ds_read_b64 v[182:183], v199
	ds_read_b128 v[166:169], v195
	ds_read_b128 v[170:173], v196
	ds_read_b128 v[174:177], v197
	ds_read_b128 v[178:181], v198
	s_ashr_i32 s77, s8, 4
	s_sub_i32 s77, 64, s77
	s_sub_i32 s78, s40, s8
	s_ashr_i32 s78, s78, 4
	s_add_i32 s78, s78, 64
	v_cndmask_b32_e64 v36, v36, v230, s[52:53]
	s_waitcnt lgkmcnt(0)
	s_add_i32 s93, s76, 0x200
	s_mov_b32 m0, s12
	v_add_u32_e32 v164, s93, v231
	v_med3_i32 v164, v164, 0, s40
	v_lshl_or_b32 v164, v164, 7, v222
	global_load_lds_dwordx4 v164, s[24:25]
	s_add_i32 m0, s12, 0x400
	v_add_u32_e32 v165, s93, v232
	v_med3_i32 v165, v165, 0, s40
	v_lshl_or_b32 v165, v165, 7, v222
	global_load_lds_dwordx4 v165, s[24:25]
	s_waitcnt vmcnt(8)
	v_add_u32_e32 v154, s13, v225
	v_add_u32_e32 v155, s13, v226
	v_add_u32_e32 v156, s13, v227
	v_add_u32_e32 v157, s13, v228
	ds_read_b64_tr_b16 v[88:89], v154
	ds_read_b64_tr_b16 v[90:91], v155
	ds_read_b64_tr_b16 v[92:93], v156
	ds_read_b64_tr_b16 v[94:95], v157
	v_mfma_f32_16x16x16_bf16 v[96:99], v[202:203], v[4:5], v[96:99]
	v_mfma_f32_16x16x16_bf16 v[100:103], v[204:205], v[4:5], v[100:103]
	v_mfma_f32_16x16x16_bf16 v[104:107], v[206:207], v[4:5], v[104:107]
	v_mfma_f32_16x16x16_bf16 v[108:111], v[208:209], v[4:5], v[108:111]
	v_cndmask_b32_e64 v68, v68, v230, s[62:63]
	v_cndmask_b32_e64 v37, v37, v230, s[56:57]
	v_cndmask_b32_e64 v69, v69, v230, s[64:65]
	v_cndmask_b32_e64 v38, v38, v230, s[58:59]
	v_cndmask_b32_e64 v70, v70, v230, s[70:71]
	v_cndmask_b32_e64 v39, v39, v230, s[60:61]
	v_cndmask_b32_e64 v71, v71, v230, s[72:73]
	v_sub_u32_e32 v200, s77, v229
	s_sub_i32 s91, s78, s77
	v_sub_u32_e32 v150, 0, v200
	v_sub_u32_e32 v151, 1, v200
	v_sub_u32_e32 v152, 2, v200
	v_sub_u32_e32 v153, 3, v200
	v_cmp_lt_u32_e64 s[94:95], s91, v150
	v_cmp_lt_u32_e64 s[86:87], s91, v151
	v_cmp_lt_u32_e64 s[0:1], s91, v152
	v_cmp_lt_u32_e64 s[2:3], s91, v153
	v_cndmask_b32_e64 v36, v36, v230, s[94:95]
	v_cndmask_b32_e64 v37, v37, v230, s[86:87]
	v_cndmask_b32_e64 v38, v38, v230, s[0:1]
	v_cndmask_b32_e64 v39, v39, v230, s[2:3]
	v_sub_u32_e32 v150, 16, v200
	v_sub_u32_e32 v151, 17, v200
	v_sub_u32_e32 v152, 18, v200
	v_sub_u32_e32 v153, 19, v200
	v_cmp_lt_u32_e64 s[94:95], s91, v150
	v_cmp_lt_u32_e64 s[86:87], s91, v151
	v_cmp_lt_u32_e64 s[0:1], s91, v152
	v_cmp_lt_u32_e64 s[2:3], s91, v153
	v_cndmask_b32_e64 v40, v40, v230, s[94:95]
	v_cndmask_b32_e64 v41, v41, v230, s[86:87]
	s_waitcnt lgkmcnt(0)
	s_add_i32 s93, s76, 0x300
	s_mov_b32 m0, s13
	v_add_u32_e32 v164, s93, v231
	v_med3_i32 v164, v164, 0, s40
	v_lshl_or_b32 v164, v164, 7, v222
	global_load_lds_dwordx4 v164, s[24:25]
	s_add_i32 m0, s13, 0x400
	v_add_u32_e32 v165, s93, v232
	v_med3_i32 v165, v165, 0, s40
	v_lshl_or_b32 v165, v165, 7, v222
	global_load_lds_dwordx4 v165, s[24:25]
	s_waitcnt vmcnt(8)
	v_add_u32_e32 v154, s14, v225
	v_add_u32_e32 v155, s14, v226
	v_add_u32_e32 v156, s14, v227
	v_add_u32_e32 v157, s14, v228
	ds_read_b64_tr_b16 v[202:203], v154
	ds_read_b64_tr_b16 v[204:205], v155
	ds_read_b64_tr_b16 v[206:207], v156
	ds_read_b64_tr_b16 v[208:209], v157
	v_mfma_f32_16x16x16_bf16 v[96:99], v[88:89], v[8:9], v[96:99]
	v_mfma_f32_16x16x16_bf16 v[100:103], v[90:91], v[8:9], v[100:103]
	v_mfma_f32_16x16x16_bf16 v[104:107], v[92:93], v[8:9], v[104:107]
	v_mfma_f32_16x16x16_bf16 v[108:111], v[94:95], v[8:9], v[108:111]
	v_cndmask_b32_e64 v42, v42, v230, s[0:1]
	v_cndmask_b32_e64 v43, v43, v230, s[2:3]
	v_sub_u32_e32 v150, 32, v200
	v_sub_u32_e32 v151, 33, v200
	v_sub_u32_e32 v152, 34, v200
	v_sub_u32_e32 v153, 35, v200
	v_cmp_lt_u32_e64 s[94:95], s91, v150
	v_cmp_lt_u32_e64 s[86:87], s91, v151
	v_cmp_lt_u32_e64 s[0:1], s91, v152
	v_cmp_lt_u32_e64 s[2:3], s91, v153
	v_cndmask_b32_e64 v44, v44, v230, s[94:95]
	v_cndmask_b32_e64 v45, v45, v230, s[86:87]
	v_cndmask_b32_e64 v46, v46, v230, s[0:1]
	v_cndmask_b32_e64 v47, v47, v230, s[2:3]
	v_sub_u32_e32 v150, 48, v200
	v_sub_u32_e32 v151, 49, v200
	v_sub_u32_e32 v152, 50, v200
	v_sub_u32_e32 v153, 51, v200
	v_cmp_lt_u32_e64 s[94:95], s91, v150
	v_cmp_lt_u32_e64 s[86:87], s91, v151
	v_cmp_lt_u32_e64 s[0:1], s91, v152
	v_cmp_lt_u32_e64 s[2:3], s91, v153
	v_cndmask_b32_e64 v48, v48, v230, s[94:95]
	v_cndmask_b32_e64 v49, v49, v230, s[86:87]
	v_cndmask_b32_e64 v50, v50, v230, s[0:1]
	v_cndmask_b32_e64 v51, v51, v230, s[2:3]
	v_sub_u32_e32 v150, 64, v200
	v_sub_u32_e32 v151, 0x41, v200
	v_sub_u32_e32 v152, 0x42, v200
	v_sub_u32_e32 v153, 0x43, v200
	v_cmp_lt_u32_e64 s[94:95], s91, v150
	s_waitcnt lgkmcnt(0)
	s_add_i32 s93, s76, 0x400
	s_mov_b32 m0, s14
	v_add_u32_e32 v164, s93, v231
	v_med3_i32 v164, v164, 0, s40
	v_lshl_or_b32 v164, v164, 7, v222
	global_load_lds_dwordx4 v164, s[24:25]
	s_add_i32 m0, s14, 0x400
	v_add_u32_e32 v165, s93, v232
	v_med3_i32 v165, v165, 0, s40
	v_lshl_or_b32 v165, v165, 7, v222
	global_load_lds_dwordx4 v165, s[24:25]
	s_waitcnt vmcnt(8)
	v_add_u32_e32 v154, s15, v225
	v_add_u32_e32 v155, s15, v226
	v_add_u32_e32 v156, s15, v227
	v_add_u32_e32 v157, s15, v228
	ds_read_b64_tr_b16 v[88:89], v154
	ds_read_b64_tr_b16 v[90:91], v155
	ds_read_b64_tr_b16 v[92:93], v156
	ds_read_b64_tr_b16 v[94:95], v157
	v_mfma_f32_16x16x16_bf16 v[96:99], v[202:203], v[12:13], v[96:99]
	v_mfma_f32_16x16x16_bf16 v[100:103], v[204:205], v[12:13], v[100:103]
	v_mfma_f32_16x16x16_bf16 v[104:107], v[206:207], v[12:13], v[104:107]
	v_mfma_f32_16x16x16_bf16 v[108:111], v[208:209], v[12:13], v[108:111]
	v_cmp_lt_u32_e64 s[86:87], s91, v151
	v_cmp_lt_u32_e64 s[0:1], s91, v152
	v_cmp_lt_u32_e64 s[2:3], s91, v153
	v_cndmask_b32_e64 v52, v52, v230, s[94:95]
	v_cndmask_b32_e64 v53, v53, v230, s[86:87]
	v_cndmask_b32_e64 v54, v54, v230, s[0:1]
	v_cndmask_b32_e64 v55, v55, v230, s[2:3]
	v_sub_u32_e32 v150, 0x50, v200
	v_sub_u32_e32 v151, 0x51, v200
	v_sub_u32_e32 v152, 0x52, v200
	v_sub_u32_e32 v153, 0x53, v200
	v_cmp_lt_u32_e64 s[94:95], s91, v150
	v_cmp_lt_u32_e64 s[86:87], s91, v151
	v_cmp_lt_u32_e64 s[0:1], s91, v152
	v_cmp_lt_u32_e64 s[2:3], s91, v153
	v_cndmask_b32_e64 v56, v56, v230, s[94:95]
	v_cndmask_b32_e64 v57, v57, v230, s[86:87]
	v_cndmask_b32_e64 v58, v58, v230, s[0:1]
	v_cndmask_b32_e64 v59, v59, v230, s[2:3]
	v_sub_u32_e32 v150, 0x60, v200
	v_sub_u32_e32 v151, 0x61, v200
	v_sub_u32_e32 v152, 0x62, v200
	v_sub_u32_e32 v153, 0x63, v200
	v_cmp_lt_u32_e64 s[94:95], s91, v150
	v_cmp_lt_u32_e64 s[86:87], s91, v151
	v_cmp_lt_u32_e64 s[0:1], s91, v152
	v_cmp_lt_u32_e64 s[2:3], s91, v153
	v_cndmask_b32_e64 v60, v60, v230, s[94:95]
	v_cndmask_b32_e64 v61, v61, v230, s[86:87]
	v_cndmask_b32_e64 v62, v62, v230, s[0:1]
	v_cndmask_b32_e64 v63, v63, v230, s[2:3]
	s_waitcnt lgkmcnt(0)
	s_add_i32 s93, s8, 0xfffffc00
	s_mov_b32 m0, s15
	v_add_u32_e32 v164, s93, v231
	v_med3_i32 v164, v164, 0, s40
	v_lshl_or_b32 v164, v164, 7, v222
	global_load_lds_dwordx4 v164, s[24:25]
	s_add_i32 m0, s15, 0x400
	v_add_u32_e32 v165, s93, v232
	v_med3_i32 v165, v165, 0, s40
	v_lshl_or_b32 v165, v165, 7, v222
	global_load_lds_dwordx4 v165, s[24:25]
	s_waitcnt vmcnt(8)
	v_add_u32_e32 v154, s16, v225
	v_add_u32_e32 v155, s16, v226
	v_add_u32_e32 v156, s16, v227
	v_add_u32_e32 v157, s16, v228
	ds_read_b64_tr_b16 v[202:203], v154
	ds_read_b64_tr_b16 v[204:205], v155
	ds_read_b64_tr_b16 v[206:207], v156
	ds_read_b64_tr_b16 v[208:209], v157
	v_mfma_f32_16x16x16_bf16 v[96:99], v[88:89], v[16:17], v[96:99]
	v_mfma_f32_16x16x16_bf16 v[100:103], v[90:91], v[16:17], v[100:103]
	v_mfma_f32_16x16x16_bf16 v[104:107], v[92:93], v[16:17], v[104:107]
	v_mfma_f32_16x16x16_bf16 v[108:111], v[94:95], v[16:17], v[108:111]
	v_sub_u32_e32 v150, 0x70, v200
	v_sub_u32_e32 v151, 0x71, v200
	v_sub_u32_e32 v152, 0x72, v200
	v_sub_u32_e32 v153, 0x73, v200
	v_cmp_lt_u32_e64 s[94:95], s91, v150
	v_cmp_lt_u32_e64 s[86:87], s91, v151
	v_cmp_lt_u32_e64 s[0:1], s91, v152
	v_cmp_lt_u32_e64 s[2:3], s91, v153
	v_cndmask_b32_e64 v64, v64, v230, s[94:95]
	v_cndmask_b32_e64 v65, v65, v230, s[86:87]
	v_cndmask_b32_e64 v66, v66, v230, s[0:1]
	v_cndmask_b32_e64 v67, v67, v230, s[2:3]
	v_sub_u32_e32 v150, 0x80, v200
	v_sub_u32_e32 v151, 0x81, v200
	v_sub_u32_e32 v152, 0x82, v200
	v_sub_u32_e32 v153, 0x83, v200
	v_cmp_lt_u32_e64 s[94:95], s91, v150
	v_cmp_lt_u32_e64 s[86:87], s91, v151
	v_cmp_lt_u32_e64 s[0:1], s91, v152
	v_cmp_lt_u32_e64 s[2:3], s91, v153
	v_cndmask_b32_e64 v68, v68, v230, s[94:95]
	v_cndmask_b32_e64 v69, v69, v230, s[86:87]
	v_cndmask_b32_e64 v70, v70, v230, s[0:1]
	v_cndmask_b32_e64 v71, v71, v230, s[2:3]
	v_max3_f32 v186, v36, v37, v38
	v_max3_f32 v186, v186, v39, v40
	v_max3_f32 v186, v186, v41, v42
	v_max3_f32 v186, v186, v43, v44
	v_max3_f32 v186, v186, v45, v46
	v_max3_f32 v186, v186, v47, v48
	v_max3_f32 v186, v186, v49, v50
	s_waitcnt lgkmcnt(0)
	s_add_i32 s93, s8, 0xfffffd00
	s_mov_b32 m0, s16
	v_add_u32_e32 v164, s93, v231
	v_med3_i32 v164, v164, 0, s40
	v_lshl_or_b32 v164, v164, 7, v222
	global_load_lds_dwordx4 v164, s[24:25]
	s_add_i32 m0, s16, 0x400
	v_add_u32_e32 v165, s93, v232
	v_med3_i32 v165, v165, 0, s40
	v_lshl_or_b32 v165, v165, 7, v222
	global_load_lds_dwordx4 v165, s[24:25]
	s_waitcnt vmcnt(8)
	v_add_u32_e32 v154, s12, v225
	v_add_u32_e32 v155, s12, v226
	v_add_u32_e32 v156, s12, v227
	v_add_u32_e32 v157, s12, v228
	ds_read_b64_tr_b16 v[88:89], v154
	ds_read_b64_tr_b16 v[90:91], v155
	ds_read_b64_tr_b16 v[92:93], v156
	ds_read_b64_tr_b16 v[94:95], v157
	v_mfma_f32_16x16x16_bf16 v[96:99], v[202:203], v[20:21], v[96:99]
	v_mfma_f32_16x16x16_bf16 v[100:103], v[204:205], v[20:21], v[100:103]
	v_mfma_f32_16x16x16_bf16 v[104:107], v[206:207], v[20:21], v[104:107]
	v_mfma_f32_16x16x16_bf16 v[108:111], v[208:209], v[20:21], v[108:111]
	v_max3_f32 v186, v186, v51, v52
	v_max3_f32 v186, v186, v53, v54
	v_max3_f32 v186, v186, v55, v56
	v_max3_f32 v186, v186, v57, v58
	v_max3_f32 v186, v186, v59, v60
	v_max3_f32 v186, v186, v61, v62
	v_max3_f32 v186, v186, v63, v64
	v_max3_f32 v186, v186, v65, v66
	v_max3_f32 v186, v186, v67, v68
	v_max3_f32 v186, v186, v69, v70
	v_max_f32_e32 v186, v186, v71
	v_mov_b32_e32 v146, v186
	s_nop 1
	v_permlane16_swap_b32_e32 v186, v146
	v_max_f32_e32 v186, v186, v146
	v_mov_b32_e32 v146, v186
	s_nop 1
	v_permlane32_swap_b32_e32 v186, v146
	v_max_f32_e32 v186, v186, v146
	v_pk_add_f32 v[36:37], v[36:37], v[186:187] op_sel_hi:[1,0] neg_lo:[0,1] neg_hi:[0,1]
	v_pk_add_f32 v[38:39], v[38:39], v[186:187] op_sel_hi:[1,0] neg_lo:[0,1] neg_hi:[0,1]
	v_pk_add_f32 v[40:41], v[40:41], v[186:187] op_sel_hi:[1,0] neg_lo:[0,1] neg_hi:[0,1]
	v_pk_add_f32 v[42:43], v[42:43], v[186:187] op_sel_hi:[1,0] neg_lo:[0,1] neg_hi:[0,1]
	v_exp_f32_e32 v36, v36
	v_exp_f32_e32 v37, v37
	v_exp_f32_e32 v38, v38
	v_exp_f32_e32 v39, v39
	v_pk_add_f32 v[44:45], v[44:45], v[186:187] op_sel_hi:[1,0] neg_lo:[0,1] neg_hi:[0,1]
	v_pk_add_f32 v[46:47], v[46:47], v[186:187] op_sel_hi:[1,0] neg_lo:[0,1] neg_hi:[0,1]
	v_exp_f32_e32 v40, v40
	v_exp_f32_e32 v41, v41
	v_exp_f32_e32 v42, v42
	v_exp_f32_e32 v43, v43
	s_waitcnt lgkmcnt(0)
	s_add_i32 s93, s8, 0xfffffe00
	s_mov_b32 m0, s12
	v_add_u32_e32 v164, s93, v231
	v_med3_i32 v164, v164, 0, s40
	v_lshl_or_b32 v164, v164, 7, v222
	global_load_lds_dwordx4 v164, s[24:25]
	s_add_i32 m0, s12, 0x400
	v_add_u32_e32 v165, s93, v232
	v_med3_i32 v165, v165, 0, s40
	v_lshl_or_b32 v165, v165, 7, v222
	global_load_lds_dwordx4 v165, s[24:25]
	s_waitcnt vmcnt(8)
	v_add_u32_e32 v154, s13, v225
	v_add_u32_e32 v155, s13, v226
	v_add_u32_e32 v156, s13, v227
	v_add_u32_e32 v157, s13, v228
	ds_read_b64_tr_b16 v[202:203], v154
	ds_read_b64_tr_b16 v[204:205], v155
	ds_read_b64_tr_b16 v[206:207], v156
	ds_read_b64_tr_b16 v[208:209], v157
	v_mfma_f32_16x16x16_bf16 v[96:99], v[88:89], v[24:25], v[96:99]
	v_mfma_f32_16x16x16_bf16 v[100:103], v[90:91], v[24:25], v[100:103]
	v_mfma_f32_16x16x16_bf16 v[104:107], v[92:93], v[24:25], v[104:107]
	v_mfma_f32_16x16x16_bf16 v[108:111], v[94:95], v[24:25], v[108:111]
	v_pk_add_f32 v[48:49], v[48:49], v[186:187] op_sel_hi:[1,0] neg_lo:[0,1] neg_hi:[0,1]
	v_pk_add_f32 v[50:51], v[50:51], v[186:187] op_sel_hi:[1,0] neg_lo:[0,1] neg_hi:[0,1]
	v_exp_f32_e32 v44, v44
	v_exp_f32_e32 v45, v45
	v_exp_f32_e32 v46, v46
	v_exp_f32_e32 v47, v47
	v_pk_add_f32 v[52:53], v[52:53], v[186:187] op_sel_hi:[1,0] neg_lo:[0,1] neg_hi:[0,1]
	v_pk_add_f32 v[54:55], v[54:55], v[186:187] op_sel_hi:[1,0] neg_lo:[0,1] neg_hi:[0,1]
	v_exp_f32_e32 v48, v48
	v_exp_f32_e32 v49, v49
	v_exp_f32_e32 v50, v50
	v_exp_f32_e32 v51, v51
	v_pk_add_f32 v[56:57], v[56:57], v[186:187] op_sel_hi:[1,0] neg_lo:[0,1] neg_hi:[0,1]
	v_pk_add_f32 v[58:59], v[58:59], v[186:187] op_sel_hi:[1,0] neg_lo:[0,1] neg_hi:[0,1]
	v_exp_f32_e32 v52, v52
	v_exp_f32_e32 v53, v53
	v_exp_f32_e32 v54, v54
	v_exp_f32_e32 v55, v55
	v_pk_add_f32 v[60:61], v[60:61], v[186:187] op_sel_hi:[1,0] neg_lo:[0,1] neg_hi:[0,1]
	v_pk_add_f32 v[62:63], v[62:63], v[186:187] op_sel_hi:[1,0] neg_lo:[0,1] neg_hi:[0,1]
	v_exp_f32_e32 v56, v56
	v_exp_f32_e32 v57, v57
	v_exp_f32_e32 v58, v58
	v_exp_f32_e32 v59, v59
	v_pk_add_f32 v[64:65], v[64:65], v[186:187] op_sel_hi:[1,0] neg_lo:[0,1] neg_hi:[0,1]
	v_pk_add_f32 v[66:67], v[66:67], v[186:187] op_sel_hi:[1,0] neg_lo:[0,1] neg_hi:[0,1]
	v_exp_f32_e32 v60, v60
	v_exp_f32_e32 v61, v61
	v_exp_f32_e32 v62, v62
	v_exp_f32_e32 v63, v63
	v_pk_add_f32 v[68:69], v[68:69], v[186:187] op_sel_hi:[1,0] neg_lo:[0,1] neg_hi:[0,1]
	s_waitcnt lgkmcnt(0)
	s_add_i32 s93, s8, 0xffffff00
	s_mov_b32 m0, s13
	v_add_u32_e32 v164, s93, v231
	v_med3_i32 v164, v164, 0, s40
	v_lshl_or_b32 v164, v164, 7, v222
	global_load_lds_dwordx4 v164, s[24:25]
	s_add_i32 m0, s13, 0x400
	v_add_u32_e32 v165, s93, v232
	v_med3_i32 v165, v165, 0, s40
	v_lshl_or_b32 v165, v165, 7, v222
	global_load_lds_dwordx4 v165, s[24:25]
	s_waitcnt vmcnt(8)
	v_add_u32_e32 v154, s14, v225
	v_add_u32_e32 v155, s14, v226
	v_add_u32_e32 v156, s14, v227
	v_add_u32_e32 v157, s14, v228
	ds_read_b64_tr_b16 v[88:89], v154
	ds_read_b64_tr_b16 v[90:91], v155
	ds_read_b64_tr_b16 v[92:93], v156
	ds_read_b64_tr_b16 v[94:95], v157
	v_mfma_f32_16x16x16_bf16 v[96:99], v[202:203], v[28:29], v[96:99]
	v_mfma_f32_16x16x16_bf16 v[100:103], v[204:205], v[28:29], v[100:103]
	v_mfma_f32_16x16x16_bf16 v[104:107], v[206:207], v[28:29], v[104:107]
	v_mfma_f32_16x16x16_bf16 v[108:111], v[208:209], v[28:29], v[108:111]
	v_pk_add_f32 v[70:71], v[70:71], v[186:187] op_sel_hi:[1,0] neg_lo:[0,1] neg_hi:[0,1]
	v_exp_f32_e32 v64, v64
	v_exp_f32_e32 v65, v65
	v_exp_f32_e32 v66, v66
	v_exp_f32_e32 v67, v67
	v_exp_f32_e32 v68, v68
	v_exp_f32_e32 v69, v69
	v_exp_f32_e32 v70, v70
	v_exp_f32_e32 v71, v71
	s_nop 0
	v_pk_add_f32 v[146:147], v[36:37], v[38:39]
	v_pk_add_f32 v[148:149], v[40:41], v[42:43]
	v_pk_add_f32 v[146:147], v[146:147], v[44:45]
	v_pk_add_f32 v[148:149], v[148:149], v[46:47]
	v_pk_add_f32 v[146:147], v[146:147], v[48:49]
	v_pk_add_f32 v[148:149], v[148:149], v[50:51]
	v_pk_add_f32 v[146:147], v[146:147], v[52:53]
	v_pk_add_f32 v[148:149], v[148:149], v[54:55]
	v_pk_add_f32 v[146:147], v[146:147], v[56:57]
	v_pk_add_f32 v[148:149], v[148:149], v[58:59]
	v_pk_add_f32 v[146:147], v[146:147], v[60:61]
	v_pk_add_f32 v[148:149], v[148:149], v[62:63]
	v_pk_add_f32 v[146:147], v[146:147], v[64:65]
	v_pk_add_f32 v[148:149], v[148:149], v[66:67]
	v_pk_add_f32 v[146:147], v[146:147], v[68:69]
	v_pk_add_f32 v[148:149], v[148:149], v[70:71]
	s_nop 0
	v_pk_add_f32 v[146:147], v[146:147], v[148:149]
	s_nop 0
	v_add_f32_e32 v187, v146, v147
	v_cvt_pk_bf16_f32 v36, v36, v37
	s_waitcnt lgkmcnt(0)
	s_add_i32 s93, s8, 0
	s_mov_b32 m0, s14
	v_add_u32_e32 v164, s93, v231
	v_med3_i32 v164, v164, 0, s40
	v_lshl_or_b32 v164, v164, 7, v222
	global_load_lds_dwordx4 v164, s[24:25]
	s_add_i32 m0, s14, 0x400
	v_add_u32_e32 v165, s93, v232
	v_med3_i32 v165, v165, 0, s40
	v_lshl_or_b32 v165, v165, 7, v222
	global_load_lds_dwordx4 v165, s[24:25]
	s_waitcnt vmcnt(8)
	v_add_u32_e32 v154, s15, v225
	v_add_u32_e32 v155, s15, v226
	v_add_u32_e32 v156, s15, v227
	v_add_u32_e32 v157, s15, v228
	ds_read_b64_tr_b16 v[202:203], v154
	ds_read_b64_tr_b16 v[204:205], v155
	ds_read_b64_tr_b16 v[206:207], v156
	ds_read_b64_tr_b16 v[208:209], v157
	v_mfma_f32_16x16x16_bf16 v[96:99], v[88:89], v[32:33], v[96:99]
	v_mfma_f32_16x16x16_bf16 v[100:103], v[90:91], v[32:33], v[100:103]
	v_mfma_f32_16x16x16_bf16 v[104:107], v[92:93], v[32:33], v[104:107]
	v_mfma_f32_16x16x16_bf16 v[108:111], v[94:95], v[32:33], v[108:111]
	v_cvt_pk_bf16_f32 v37, v38, v39
	v_cvt_pk_bf16_f32 v40, v40, v41
	v_cvt_pk_bf16_f32 v41, v42, v43
	v_cvt_pk_bf16_f32 v44, v44, v45
	v_cvt_pk_bf16_f32 v45, v46, v47
	v_cvt_pk_bf16_f32 v48, v48, v49
	v_cvt_pk_bf16_f32 v49, v50, v51
	v_cvt_pk_bf16_f32 v52, v52, v53
	v_cvt_pk_bf16_f32 v53, v54, v55
	v_cvt_pk_bf16_f32 v56, v56, v57
	v_cvt_pk_bf16_f32 v57, v58, v59
	v_cvt_pk_bf16_f32 v60, v60, v61
	v_cvt_pk_bf16_f32 v61, v62, v63
	v_cvt_pk_bf16_f32 v64, v64, v65
	v_cvt_pk_bf16_f32 v65, v66, v67
	v_cvt_pk_bf16_f32 v68, v68, v69
	v_cvt_pk_bf16_f32 v69, v70, v71
	v_mov_b32_e32 v146, v187
	s_nop 1
	v_permlane16_swap_b32_e32 v187, v146
	v_add_f32_e32 v187, v187, v146
	v_mov_b32_e32 v146, v187
	s_nop 1
	v_permlane32_swap_b32_e32 v187, v146
	v_add_f32_e32 v187, v187, v146
	s_waitcnt lgkmcnt(0)
	s_add_i32 s93, s8, 0x100
	s_mov_b32 m0, s15
	v_add_u32_e32 v164, s93, v231
	v_med3_i32 v164, v164, 0, s40
	v_lshl_or_b32 v164, v164, 7, v222
	global_load_lds_dwordx4 v164, s[24:25]
	s_add_i32 m0, s15, 0x400
	v_add_u32_e32 v165, s93, v232
	v_med3_i32 v165, v165, 0, s40
	v_lshl_or_b32 v165, v165, 7, v222
	global_load_lds_dwordx4 v165, s[24:25]
	s_waitcnt vmcnt(8)
	v_add_u32_e32 v154, s16, v225
	v_add_u32_e32 v155, s16, v226
	v_add_u32_e32 v156, s16, v227
	v_add_u32_e32 v157, s16, v228
	ds_read_b64_tr_b16 v[88:89], v154
	ds_read_b64_tr_b16 v[90:91], v155
	ds_read_b64_tr_b16 v[92:93], v156
	ds_read_b64_tr_b16 v[94:95], v157
	v_mfma_f32_16x16x16_bf16 v[112:115], v[202:203], v[36:37], 0
	v_mfma_f32_16x16x16_bf16 v[116:119], v[204:205], v[36:37], 0
	v_mfma_f32_16x16x16_bf16 v[120:123], v[206:207], v[36:37], 0
	v_mfma_f32_16x16x16_bf16 v[124:127], v[208:209], v[36:37], 0
	s_waitcnt lgkmcnt(0)
	s_add_i32 s93, s8, 0x200
	s_mov_b32 m0, s16
	v_add_u32_e32 v164, s93, v231
	v_med3_i32 v164, v164, 0, s40
	v_lshl_or_b32 v164, v164, 7, v222
	global_load_lds_dwordx4 v164, s[24:25]
	s_add_i32 m0, s16, 0x400
	v_add_u32_e32 v165, s93, v232
	v_med3_i32 v165, v165, 0, s40
	v_lshl_or_b32 v165, v165, 7, v222
	global_load_lds_dwordx4 v165, s[24:25]
	s_waitcnt vmcnt(8)
	v_add_u32_e32 v154, s12, v225
	v_add_u32_e32 v155, s12, v226
	v_add_u32_e32 v156, s12, v227
	v_add_u32_e32 v157, s12, v228
	ds_read_b64_tr_b16 v[202:203], v154
	ds_read_b64_tr_b16 v[204:205], v155
	ds_read_b64_tr_b16 v[206:207], v156
	ds_read_b64_tr_b16 v[208:209], v157
	v_mfma_f32_16x16x16_bf16 v[112:115], v[88:89], v[40:41], v[112:115]
	v_mfma_f32_16x16x16_bf16 v[116:119], v[90:91], v[40:41], v[116:119]
	v_mfma_f32_16x16x16_bf16 v[120:123], v[92:93], v[40:41], v[120:123]
	v_mfma_f32_16x16x16_bf16 v[124:127], v[94:95], v[40:41], v[124:127]
	s_waitcnt lgkmcnt(0)
	s_add_i32 s93, s8, 0x300
	s_mov_b32 m0, s12
	v_add_u32_e32 v164, s93, v231
	v_med3_i32 v164, v164, 0, s40
	v_lshl_or_b32 v164, v164, 7, v222
	global_load_lds_dwordx4 v164, s[24:25]
	s_add_i32 m0, s12, 0x400
	v_add_u32_e32 v165, s93, v232
	v_med3_i32 v165, v165, 0, s40
	v_lshl_or_b32 v165, v165, 7, v222
	global_load_lds_dwordx4 v165, s[24:25]
	s_waitcnt vmcnt(8)
	v_add_u32_e32 v154, s13, v225
	v_add_u32_e32 v155, s13, v226
	v_add_u32_e32 v156, s13, v227
	v_add_u32_e32 v157, s13, v228
	ds_read_b64_tr_b16 v[88:89], v154
	ds_read_b64_tr_b16 v[90:91], v155
	ds_read_b64_tr_b16 v[92:93], v156
	ds_read_b64_tr_b16 v[94:95], v157
	v_mfma_f32_16x16x16_bf16 v[112:115], v[202:203], v[44:45], v[112:115]
	v_mfma_f32_16x16x16_bf16 v[116:119], v[204:205], v[44:45], v[116:119]
	v_mfma_f32_16x16x16_bf16 v[120:123], v[206:207], v[44:45], v[120:123]
	v_mfma_f32_16x16x16_bf16 v[124:127], v[208:209], v[44:45], v[124:127]
	s_waitcnt lgkmcnt(0)
	s_add_i32 s93, s8, 0x400
	s_mov_b32 m0, s13
	v_add_u32_e32 v164, s93, v231
	v_med3_i32 v164, v164, 0, s40
	v_lshl_or_b32 v164, v164, 7, v222
	global_load_lds_dwordx4 v164, s[24:25]
	s_add_i32 m0, s13, 0x400
	v_add_u32_e32 v165, s93, v232
	v_med3_i32 v165, v165, 0, s40
	v_lshl_or_b32 v165, v165, 7, v222
	global_load_lds_dwordx4 v165, s[24:25]
	s_waitcnt vmcnt(8)
	v_add_u32_e32 v154, s14, v225
	v_add_u32_e32 v155, s14, v226
	v_add_u32_e32 v156, s14, v227
	v_add_u32_e32 v157, s14, v228
	ds_read_b64_tr_b16 v[202:203], v154
	ds_read_b64_tr_b16 v[204:205], v155
	ds_read_b64_tr_b16 v[206:207], v156
	ds_read_b64_tr_b16 v[208:209], v157
	v_mfma_f32_16x16x16_bf16 v[112:115], v[88:89], v[48:49], v[112:115]
	v_mfma_f32_16x16x16_bf16 v[116:119], v[90:91], v[48:49], v[116:119]
	v_mfma_f32_16x16x16_bf16 v[120:123], v[92:93], v[48:49], v[120:123]
	v_mfma_f32_16x16x16_bf16 v[124:127], v[94:95], v[48:49], v[124:127]
	s_waitcnt lgkmcnt(0)
	s_add_i32 s93, s79, 0
	s_mov_b32 m0, s14
	v_add_u32_e32 v164, s93, v162
	v_lshl_or_b32 v164, v164, 7, v220
	global_load_lds_dwordx4 v164, s[30:31]
	s_add_i32 m0, s14, 0x400
	v_add_u32_e32 v165, s93, v163
	v_lshl_or_b32 v165, v165, 7, v221
	global_load_lds_dwordx4 v165, s[30:31]
	s_waitcnt vmcnt(8)
	v_add_u32_e32 v154, s15, v225
	v_add_u32_e32 v155, s15, v226
	v_add_u32_e32 v156, s15, v227
	v_add_u32_e32 v157, s15, v228
	ds_read_b64_tr_b16 v[88:89], v154
	ds_read_b64_tr_b16 v[90:91], v155
	ds_read_b64_tr_b16 v[92:93], v156
	ds_read_b64_tr_b16 v[94:95], v157
	v_mfma_f32_16x16x16_bf16 v[112:115], v[202:203], v[52:53], v[112:115]
	v_mfma_f32_16x16x16_bf16 v[116:119], v[204:205], v[52:53], v[116:119]
	v_mfma_f32_16x16x16_bf16 v[120:123], v[206:207], v[52:53], v[120:123]
	v_mfma_f32_16x16x16_bf16 v[124:127], v[208:209], v[52:53], v[124:127]
	s_waitcnt lgkmcnt(0)
	s_add_i32 s93, s79, 16
	s_mov_b32 m0, s15
	v_add_u32_e32 v164, s93, v162
	v_lshl_or_b32 v164, v164, 7, v220
	global_load_lds_dwordx4 v164, s[30:31]
	s_add_i32 m0, s15, 0x400
	v_add_u32_e32 v165, s93, v163
	v_lshl_or_b32 v165, v165, 7, v221
	global_load_lds_dwordx4 v165, s[30:31]
	s_waitcnt vmcnt(8)
	v_add_u32_e32 v154, s16, v225
	v_add_u32_e32 v155, s16, v226
	v_add_u32_e32 v156, s16, v227
	v_add_u32_e32 v157, s16, v228
	ds_read_b64_tr_b16 v[202:203], v154
	ds_read_b64_tr_b16 v[204:205], v155
	ds_read_b64_tr_b16 v[206:207], v156
	ds_read_b64_tr_b16 v[208:209], v157
	v_mfma_f32_16x16x16_bf16 v[112:115], v[88:89], v[56:57], v[112:115]
	v_mfma_f32_16x16x16_bf16 v[116:119], v[90:91], v[56:57], v[116:119]
	v_mfma_f32_16x16x16_bf16 v[120:123], v[92:93], v[56:57], v[120:123]
	v_mfma_f32_16x16x16_bf16 v[124:127], v[94:95], v[56:57], v[124:127]
	s_waitcnt lgkmcnt(0)
	s_add_i32 s93, s79, 0xffffffc0
	s_mov_b32 m0, s16
	v_add_u32_e32 v164, s93, v162
	v_med3_i32 v164, v164, 0, s41
	v_lshl_or_b32 v164, v164, 7, v220
	global_load_lds_dwordx4 v164, s[34:35]
	s_add_i32 m0, s16, 0x400
	v_add_u32_e32 v165, s93, v163
	v_med3_i32 v165, v165, 0, s41
	v_lshl_or_b32 v165, v165, 7, v221
	global_load_lds_dwordx4 v165, s[34:35]
	s_waitcnt vmcnt(8)
	v_add_u32_e32 v154, s12, v225
	v_add_u32_e32 v155, s12, v226
	v_add_u32_e32 v156, s12, v227
	v_add_u32_e32 v157, s12, v228
	ds_read_b64_tr_b16 v[88:89], v154
	ds_read_b64_tr_b16 v[90:91], v155
	ds_read_b64_tr_b16 v[92:93], v156
	ds_read_b64_tr_b16 v[94:95], v157
	v_mfma_f32_16x16x16_bf16 v[112:115], v[202:203], v[60:61], v[112:115]
	v_mfma_f32_16x16x16_bf16 v[116:119], v[204:205], v[60:61], v[116:119]
	v_mfma_f32_16x16x16_bf16 v[120:123], v[206:207], v[60:61], v[120:123]
	v_mfma_f32_16x16x16_bf16 v[124:127], v[208:209], v[60:61], v[124:127]
	s_waitcnt lgkmcnt(0)
	s_add_i32 s93, s79, 0xffffffd0
	s_mov_b32 m0, s12
	v_add_u32_e32 v164, s93, v162
	v_med3_i32 v164, v164, 0, s41
	v_lshl_or_b32 v164, v164, 7, v220
	global_load_lds_dwordx4 v164, s[34:35]
	s_add_i32 m0, s12, 0x400
	v_add_u32_e32 v165, s93, v163
	v_med3_i32 v165, v165, 0, s41
	v_lshl_or_b32 v165, v165, 7, v221
	global_load_lds_dwordx4 v165, s[34:35]
	s_waitcnt vmcnt(8)
	v_add_u32_e32 v154, s13, v225
	v_add_u32_e32 v155, s13, v226
	v_add_u32_e32 v156, s13, v227
	v_add_u32_e32 v157, s13, v228
	ds_read_b64_tr_b16 v[202:203], v154
	ds_read_b64_tr_b16 v[204:205], v155
	ds_read_b64_tr_b16 v[206:207], v156
	ds_read_b64_tr_b16 v[208:209], v157
	v_mfma_f32_16x16x16_bf16 v[112:115], v[88:89], v[64:65], v[112:115]
	v_mfma_f32_16x16x16_bf16 v[116:119], v[90:91], v[64:65], v[116:119]
	v_mfma_f32_16x16x16_bf16 v[120:123], v[92:93], v[64:65], v[120:123]
	v_mfma_f32_16x16x16_bf16 v[124:127], v[94:95], v[64:65], v[124:127]
	s_waitcnt lgkmcnt(0)
	s_add_i32 s93, s79, 0xffffffe0
	s_mov_b32 m0, s13
	v_add_u32_e32 v164, s93, v162
	v_med3_i32 v164, v164, 0, s41
	v_lshl_or_b32 v164, v164, 7, v220
	global_load_lds_dwordx4 v164, s[34:35]
	s_add_i32 m0, s13, 0x400
	v_add_u32_e32 v165, s93, v163
	v_med3_i32 v165, v165, 0, s41
	v_lshl_or_b32 v165, v165, 7, v221
	global_load_lds_dwordx4 v165, s[34:35]
	v_mfma_f32_16x16x16_bf16 v[112:115], v[202:203], v[68:69], v[112:115]
	v_mfma_f32_16x16x16_bf16 v[116:119], v[204:205], v[68:69], v[116:119]
	v_mfma_f32_16x16x16_bf16 v[120:123], v[206:207], v[68:69], v[120:123]
	v_mfma_f32_16x16x16_bf16 v[124:127], v[208:209], v[68:69], v[124:127]
	s_waitcnt lgkmcnt(0)
	v_max_f32_e32 v146, v144, v184
	v_sub_f32_e32 v148, v144, v146
	v_sub_f32_e32 v150, v184, v146
	v_exp_f32_e32 v148, v148
	v_exp_f32_e32 v150, v150
	v_mov_b32_e32 v184, v146
	v_mul_f32_e32 v185, v185, v150
	v_fmac_f32_e32 v185, v145, v148
	v_pk_mul_f32 v[96:97], v[150:151], v[96:97] op_sel_hi:[0,1]
	v_pk_mul_f32 v[98:99], v[150:151], v[98:99] op_sel_hi:[0,1]
	v_pk_mul_f32 v[100:101], v[150:151], v[100:101] op_sel_hi:[0,1]
	v_pk_mul_f32 v[102:103], v[150:151], v[102:103] op_sel_hi:[0,1]
	v_pk_mul_f32 v[104:105], v[150:151], v[104:105] op_sel_hi:[0,1]
	v_pk_mul_f32 v[106:107], v[150:151], v[106:107] op_sel_hi:[0,1]
	v_pk_mul_f32 v[108:109], v[150:151], v[108:109] op_sel_hi:[0,1]
	v_pk_mul_f32 v[110:111], v[150:151], v[110:111] op_sel_hi:[0,1]
	v_pk_fma_f32 v[96:97], v[148:149], v[128:129], v[96:97] op_sel_hi:[0,1,1]
	v_pk_fma_f32 v[98:99], v[148:149], v[130:131], v[98:99] op_sel_hi:[0,1,1]
	v_pk_fma_f32 v[100:101], v[148:149], v[132:133], v[100:101] op_sel_hi:[0,1,1]
	v_pk_fma_f32 v[102:103], v[148:149], v[134:135], v[102:103] op_sel_hi:[0,1,1]
	v_pk_fma_f32 v[104:105], v[148:149], v[136:137], v[104:105] op_sel_hi:[0,1,1]
	v_pk_fma_f32 v[106:107], v[148:149], v[138:139], v[106:107] op_sel_hi:[0,1,1]
	v_pk_fma_f32 v[108:109], v[148:149], v[140:141], v[108:109] op_sel_hi:[0,1,1]
	v_pk_fma_f32 v[110:111], v[148:149], v[142:143], v[110:111] op_sel_hi:[0,1,1]
	v_div_scale_f32 v147, s[94:95], v185, v185, 1.0
	v_rcp_f32_e32 v148, v147
	v_div_scale_f32 v149, vcc, 1.0, v185, 1.0
	v_fma_f32 v150, -v147, v148, 1.0
	v_fmac_f32_e32 v148, v150, v148
	v_mul_f32_e32 v150, v149, v148
	v_fma_f32 v151, -v147, v150, v149
	v_fmac_f32_e32 v150, v151, v148
	v_fma_f32 v147, -v147, v150, v149
	s_nop 1
	v_div_fmas_f32 v147, v147, v148, v150
	v_div_fixup_f32 v152, v147, v185, 1.0
	v_pk_mul_f32 v[96:97], v[152:153], v[96:97] op_sel_hi:[0,1]
	v_pk_mul_f32 v[98:99], v[152:153], v[98:99] op_sel_hi:[0,1]
	v_pk_mul_f32 v[100:101], v[152:153], v[100:101] op_sel_hi:[0,1]
	v_pk_mul_f32 v[102:103], v[152:153], v[102:103] op_sel_hi:[0,1]
	v_pk_mul_f32 v[104:105], v[152:153], v[104:105] op_sel_hi:[0,1]
	v_pk_mul_f32 v[106:107], v[152:153], v[106:107] op_sel_hi:[0,1]
	v_pk_mul_f32 v[108:109], v[152:153], v[108:109] op_sel_hi:[0,1]
	v_pk_mul_f32 v[110:111], v[152:153], v[110:111] op_sel_hi:[0,1]
	v_mul_f32_e32 v155, v97, v97
	v_mul_f32_e32 v156, v99, v99
	v_fmac_f32_e32 v155, v96, v96
	v_fmac_f32_e32 v156, v98, v98
	v_add_f32_e32 v154, v155, v156
	v_mul_f32_e32 v155, v101, v101
	v_mul_f32_e32 v156, v103, v103
	v_fmac_f32_e32 v155, v100, v100
	v_fmac_f32_e32 v156, v102, v102
	v_add_f32_e32 v155, v155, v156
	v_add_f32_e32 v154, v154, v155
	v_mul_f32_e32 v155, v105, v105
	v_mul_f32_e32 v156, v107, v107
	v_fmac_f32_e32 v155, v104, v104
	v_fmac_f32_e32 v156, v106, v106
	v_add_f32_e32 v155, v155, v156
	v_add_f32_e32 v154, v154, v155
	v_mul_f32_e32 v155, v109, v109
	v_mul_f32_e32 v156, v111, v111
	v_fmac_f32_e32 v155, v108, v108
	v_fmac_f32_e32 v156, v110, v110
	v_add_f32_e32 v155, v155, v156
	v_add_f32_e32 v154, v154, v155
	v_cvt_pk_bf16_f32 v96, v96, v97
	v_cvt_pk_bf16_f32 v97, v98, v99
	v_cvt_pk_bf16_f32 v100, v100, v101
	v_cvt_pk_bf16_f32 v101, v102, v103
	v_cvt_pk_bf16_f32 v104, v104, v105
	v_cvt_pk_bf16_f32 v105, v106, v107
	v_cvt_pk_bf16_f32 v108, v108, v109
	v_cvt_pk_bf16_f32 v109, v110, v111
	v_add_u32_e32 v157, s42, v188
	s_lshl_b32 s90, s43, 7
	v_lshlrev_b32_e32 v158, 11, v157
	v_add3_u32 v158, v158, s90, v233
	v_mov_b32_e32 v160, v96
	v_mov_b32_e32 v161, v97
	v_mov_b32_e32 v162, v100
	v_mov_b32_e32 v163, v101
	s_nop 1
	v_permlane16_swap_b32_e32 v160, v162
	v_permlane16_swap_b32_e32 v161, v163
	s_nop 1
	global_store_dwordx4 v158, v[160:163], s[48:49] offset:0
	s_nop 1
	v_mov_b32_e32 v160, v104
	v_mov_b32_e32 v161, v105
	v_mov_b32_e32 v162, v108
	v_mov_b32_e32 v163, v109
	s_nop 1
	v_permlane16_swap_b32_e32 v160, v162
	v_permlane16_swap_b32_e32 v161, v163
	s_nop 1
	global_store_dwordx4 v158, v[160:163], s[48:49] offset:64
	s_nop 1
	v_mov_b32_e32 v155, v154
	s_nop 1
	v_permlane16_swap_b32_e32 v154, v155
	v_add_f32_e32 v154, v154, v155
	v_mov_b32_e32 v155, v154
	s_nop 1
	v_permlane32_swap_b32_e32 v154, v155
	v_add_f32_e32 v154, v154, v155
	v_mul_u32_u24_e32 v157, 48, v157
	s_lshl_b32 s90, s43, 2
	v_add_u32_e32 v157, s90, v157
	s_and_saveexec_b64 s[80:81], s[74:75]
	global_store_dword v157, v154, s[50:51]
	s_mov_b64 exec, s[80:81]
	s_waitcnt lgkmcnt(0)
	v_max_f32_e32 v146, v182, v186
	v_sub_f32_e32 v148, v182, v146
	v_sub_f32_e32 v150, v186, v146
	v_exp_f32_e32 v148, v148
	v_exp_f32_e32 v150, v150
	v_mov_b32_e32 v186, v146
	v_mul_f32_e32 v187, v187, v150
	v_fmac_f32_e32 v187, v183, v148
	v_pk_mul_f32 v[112:113], v[150:151], v[112:113] op_sel_hi:[0,1]
	v_pk_mul_f32 v[114:115], v[150:151], v[114:115] op_sel_hi:[0,1]
	v_pk_mul_f32 v[116:117], v[150:151], v[116:117] op_sel_hi:[0,1]
	v_pk_mul_f32 v[118:119], v[150:151], v[118:119] op_sel_hi:[0,1]
	v_pk_mul_f32 v[120:121], v[150:151], v[120:121] op_sel_hi:[0,1]
	v_pk_mul_f32 v[122:123], v[150:151], v[122:123] op_sel_hi:[0,1]
	v_pk_mul_f32 v[124:125], v[150:151], v[124:125] op_sel_hi:[0,1]
	v_pk_mul_f32 v[126:127], v[150:151], v[126:127] op_sel_hi:[0,1]
	v_pk_fma_f32 v[112:113], v[148:149], v[166:167], v[112:113] op_sel_hi:[0,1,1]
	v_pk_fma_f32 v[114:115], v[148:149], v[168:169], v[114:115] op_sel_hi:[0,1,1]
	v_pk_fma_f32 v[116:117], v[148:149], v[170:171], v[116:117] op_sel_hi:[0,1,1]
	v_pk_fma_f32 v[118:119], v[148:149], v[172:173], v[118:119] op_sel_hi:[0,1,1]
	v_pk_fma_f32 v[120:121], v[148:149], v[174:175], v[120:121] op_sel_hi:[0,1,1]
	v_pk_fma_f32 v[122:123], v[148:149], v[176:177], v[122:123] op_sel_hi:[0,1,1]
	v_pk_fma_f32 v[124:125], v[148:149], v[178:179], v[124:125] op_sel_hi:[0,1,1]
	v_pk_fma_f32 v[126:127], v[148:149], v[180:181], v[126:127] op_sel_hi:[0,1,1]
	v_div_scale_f32 v147, s[94:95], v187, v187, 1.0
	v_rcp_f32_e32 v148, v147
	v_div_scale_f32 v149, vcc, 1.0, v187, 1.0
	v_fma_f32 v150, -v147, v148, 1.0
	v_fmac_f32_e32 v148, v150, v148
	v_mul_f32_e32 v150, v149, v148
	v_fma_f32 v151, -v147, v150, v149
	v_fmac_f32_e32 v150, v151, v148
	v_fma_f32 v147, -v147, v150, v149
	s_nop 1
	v_div_fmas_f32 v147, v147, v148, v150
	v_div_fixup_f32 v152, v147, v187, 1.0
	v_pk_mul_f32 v[112:113], v[152:153], v[112:113] op_sel_hi:[0,1]
	v_pk_mul_f32 v[114:115], v[152:153], v[114:115] op_sel_hi:[0,1]
	v_pk_mul_f32 v[116:117], v[152:153], v[116:117] op_sel_hi:[0,1]
	v_pk_mul_f32 v[118:119], v[152:153], v[118:119] op_sel_hi:[0,1]
	v_pk_mul_f32 v[120:121], v[152:153], v[120:121] op_sel_hi:[0,1]
	v_pk_mul_f32 v[122:123], v[152:153], v[122:123] op_sel_hi:[0,1]
	v_pk_mul_f32 v[124:125], v[152:153], v[124:125] op_sel_hi:[0,1]
	v_pk_mul_f32 v[126:127], v[152:153], v[126:127] op_sel_hi:[0,1]
	v_mul_f32_e32 v155, v113, v113
	v_mul_f32_e32 v156, v115, v115
	v_fmac_f32_e32 v155, v112, v112
	v_fmac_f32_e32 v156, v114, v114
	v_add_f32_e32 v154, v155, v156
	v_mul_f32_e32 v155, v117, v117
	v_mul_f32_e32 v156, v119, v119
	v_fmac_f32_e32 v155, v116, v116
	v_fmac_f32_e32 v156, v118, v118
	v_add_f32_e32 v155, v155, v156
	v_add_f32_e32 v154, v154, v155
	v_mul_f32_e32 v155, v121, v121
	v_mul_f32_e32 v156, v123, v123
	v_fmac_f32_e32 v155, v120, v120
	v_fmac_f32_e32 v156, v122, v122
	v_add_f32_e32 v155, v155, v156
	v_add_f32_e32 v154, v154, v155
	v_mul_f32_e32 v155, v125, v125
	v_mul_f32_e32 v156, v127, v127
	v_fmac_f32_e32 v155, v124, v124
	v_fmac_f32_e32 v156, v126, v126
	v_add_f32_e32 v155, v155, v156
	v_add_f32_e32 v154, v154, v155
	v_cvt_pk_bf16_f32 v112, v112, v113
	v_cvt_pk_bf16_f32 v113, v114, v115
	v_cvt_pk_bf16_f32 v116, v116, v117
	v_cvt_pk_bf16_f32 v117, v118, v119
	v_cvt_pk_bf16_f32 v120, v120, v121
	v_cvt_pk_bf16_f32 v121, v122, v123
	v_cvt_pk_bf16_f32 v124, v124, v125
	v_cvt_pk_bf16_f32 v125, v126, v127
	v_add_u32_e32 v157, s42, v189
	s_lshl_b32 s90, s43, 7
	v_lshlrev_b32_e32 v158, 11, v157
	v_add3_u32 v158, v158, s90, v233
	v_mov_b32_e32 v160, v112
	v_mov_b32_e32 v161, v113
	v_mov_b32_e32 v162, v116
	v_mov_b32_e32 v163, v117
	s_nop 1
	v_permlane16_swap_b32_e32 v160, v162
	v_permlane16_swap_b32_e32 v161, v163
	s_nop 1
	global_store_dwordx4 v158, v[160:163], s[48:49] offset:0
	s_nop 1
	v_mov_b32_e32 v160, v120
	v_mov_b32_e32 v161, v121
	v_mov_b32_e32 v162, v124
	v_mov_b32_e32 v163, v125
	s_nop 1
	v_permlane16_swap_b32_e32 v160, v162
	v_permlane16_swap_b32_e32 v161, v163
	s_nop 1
	global_store_dwordx4 v158, v[160:163], s[48:49] offset:64
	s_nop 1
	v_mov_b32_e32 v155, v154
	s_nop 1
	v_permlane16_swap_b32_e32 v154, v155
	v_add_f32_e32 v154, v154, v155
	v_mov_b32_e32 v155, v154
	s_nop 1
	v_permlane32_swap_b32_e32 v154, v155
	v_add_f32_e32 v154, v154, v155
	v_mul_u32_u24_e32 v157, 48, v157
	s_lshl_b32 s90, s43, 2
	v_add_u32_e32 v157, s90, v157
	s_and_saveexec_b64 s[80:81], s[74:75]
	global_store_dword v157, v154, s[50:51]
	s_mov_b64 exec, s[80:81]
	s_waitcnt lgkmcnt(0)
	s_barrier
	s_mov_b32 s90, s14
	s_mov_b32 s91, s15
	s_mov_b32 s92, s16
	s_mov_b32 s93, s12
	s_mov_b32 s97, s13
	s_mov_b32 s12, s90
	s_mov_b32 s13, s91
	s_mov_b32 s14, s92
	s_mov_b32 s15, s93
	s_mov_b32 s16, s97
	s_mov_b64 s[18:19], s[30:31]
	s_mov_b64 s[20:21], s[34:35]
	s_mov_b64 s[24:25], s[36:37]
	s_mov_b32 s38, s39
	s_mov_b32 s40, s41
	s_mov_b32 s42, s44
	s_mov_b32 s43, s45
	s_add_i32 s11, s11, s66
	s_cmpk_lt_u32 s11, 0x900
	s_cbranch_scc1 .Latt_unit
	v_readlane_b32 s0, v244, 20
	s_bfe_u32 s3, s0, 0x20006
